# P1 weight-conversion loops: batched the serialized global loads (8 in flight); at_unit finish gate loads batched
# speedup vs baseline: 1.0241x; 1.0239x over previous
.LBB0_220:
	v_add_u32_e32 v17, s9, v8
	v_add_u32_e32 v18, 0xffffdc00, v17
	v_ashrrev_i32_e32 v19, 31, v18
	v_lshlrev_b64 v[18:19], 12, v[18:19]
	v_lshl_add_u64 v[18:19], v[14:15], 0, v[18:19]
	global_load_dwordx4 v[18:21], v[18:19], off nt
	v_add_u32_e32 v194, 0xffffdc04, v17
	v_ashrrev_i32_e32 v195, 31, v194
	v_lshlrev_b64 v[194:195], 12, v[194:195]
	v_lshl_add_u64 v[194:195], v[14:15], 0, v[194:195]
	global_load_dwordx4 v[194:197], v[194:195], off nt
	v_add_u32_e32 v200, 0xffffdc08, v17
	v_ashrrev_i32_e32 v201, 31, v200
	v_lshlrev_b64 v[200:201], 12, v[200:201]
	v_lshl_add_u64 v[200:201], v[14:15], 0, v[200:201]
	global_load_dwordx4 v[200:203], v[200:201], off nt
	v_add_u32_e32 v210, 0xffffdc0c, v17
	v_ashrrev_i32_e32 v211, 31, v210
	v_lshlrev_b64 v[210:211], 12, v[210:211]
	v_lshl_add_u64 v[210:211], v[14:15], 0, v[210:211]
	global_load_dwordx4 v[210:213], v[210:211], off nt
	v_add_u32_e32 v216, 0xffffdc10, v17
	v_ashrrev_i32_e32 v217, 31, v216
	v_lshlrev_b64 v[216:217], 12, v[216:217]
	v_lshl_add_u64 v[216:217], v[14:15], 0, v[216:217]
	global_load_dwordx4 v[216:219], v[216:217], off nt
	v_add_u32_e32 v222, 0xffffdc14, v17
	v_ashrrev_i32_e32 v223, 31, v222
	v_lshlrev_b64 v[222:223], 12, v[222:223]
	v_lshl_add_u64 v[222:223], v[14:15], 0, v[222:223]
	global_load_dwordx4 v[222:225], v[222:223], off nt
	v_add_u32_e32 v230, 0xffffdc18, v17
	v_ashrrev_i32_e32 v231, 31, v230
	v_lshlrev_b64 v[230:231], 12, v[230:231]
	v_lshl_add_u64 v[230:231], v[14:15], 0, v[230:231]
	global_load_dwordx4 v[230:233], v[230:231], off nt
	v_add_u32_e32 v188, 0xffffdc1c, v17
	v_ashrrev_i32_e32 v189, 31, v188
	v_lshlrev_b64 v[188:189], 12, v[188:189]
	v_lshl_add_u64 v[188:189], v[14:15], 0, v[188:189]
	global_load_dwordx4 v[188:191], v[188:189], off nt
	s_waitcnt vmcnt(7)
	v_add_u32_e32 v22, 0x410, v16
	s_add_i32 s9, s9, 32
	s_cmp_lg_u32 s9, 64
	ds_write2_b32 v16, v18, v19 offset1:1
	ds_write2_b32 v16, v20, v21 offset0:2 offset1:3
	s_waitcnt vmcnt(6)
	ds_write2_b32 v22, v194, v195 offset1:1
	v_add_u32_e32 v194, 0x418, v16
	ds_write2_b32 v194, v196, v197 offset1:1
	s_waitcnt vmcnt(5)
	v_add_u32_e32 v204, 0x820, v16
	ds_write2_b32 v204, v200, v201 offset1:1
	v_add_u32_e32 v200, 0x828, v16
	ds_write2_b32 v200, v202, v203 offset1:1
	s_waitcnt vmcnt(4)
	v_add_u32_e32 v214, 0xc30, v16
	ds_write2_b32 v214, v210, v211 offset1:1
	v_add_u32_e32 v210, 0xc38, v16
	ds_write2_b32 v210, v212, v213 offset1:1
	s_waitcnt vmcnt(3)
	v_add_u32_e32 v220, 0x1040, v16
	ds_write2_b32 v220, v216, v217 offset1:1
	v_add_u32_e32 v216, 0x1048, v16
	ds_write2_b32 v216, v218, v219 offset1:1
	s_waitcnt vmcnt(2)
	v_add_u32_e32 v226, 0x1450, v16
	ds_write2_b32 v226, v222, v223 offset1:1
	v_add_u32_e32 v222, 0x1458, v16
	ds_write2_b32 v222, v224, v225 offset1:1
	s_waitcnt vmcnt(1)
	v_add_u32_e32 v234, 0x1860, v16
	ds_write2_b32 v234, v230, v231 offset1:1
	v_add_u32_e32 v230, 0x1868, v16
	ds_write2_b32 v230, v232, v233 offset1:1
	s_waitcnt vmcnt(0)
	v_add_u32_e32 v17, 0x1c70, v16
	ds_write2_b32 v17, v188, v189 offset1:1
	v_add_u32_e32 v17, 0x1c78, v16
	v_add_u32_e32 v16, 0x2080, v16
	ds_write2_b32 v17, v190, v191 offset1:1
	s_cbranch_scc1 .LBB0_220
	v_add_u32_e32 v8, 0x400, v49
	ds_read2_b32 v[20:21], v49 offset0:65 offset1:73
	ds_read2_b32 v[22:23], v49 offset1:8
	ds_read2_b32 v[24:25], v49 offset0:130 offset1:138
	ds_read2_b32 v[26:27], v49 offset0:195 offset1:203
	ds_read2_b32 v[28:29], v8 offset0:4 offset1:12
	ds_read2_b32 v[30:31], v8 offset0:69 offset1:77
	ds_read2_b32 v[32:33], v8 offset0:134 offset1:142
	ds_read2_b32 v[34:35], v8 offset0:199 offset1:207
	s_lshl_b32 s9, s21, 2
	s_and_b32 s9, s9, 0x7fffffc0
	v_add_u32_e32 v36, s8, v48
	s_add_i32 s82, s9, 0xffffdc00
	v_ashrrev_i32_e32 v37, 31, v36
	v_lshl_add_u64 v[14:15], s[82:83], 1, v[2:3]
	v_lshlrev_b64 v[36:37], 11, v[36:37]
	s_waitcnt lgkmcnt(6)
	v_cvt_pk_bf16_f32 v16, v22, v20
	s_waitcnt lgkmcnt(4)
	v_cvt_pk_bf16_f32 v17, v24, v26
	s_waitcnt lgkmcnt(2)
	v_cvt_pk_bf16_f32 v18, v28, v30
	s_waitcnt lgkmcnt(0)
	v_cvt_pk_bf16_f32 v19, v32, v34
	v_lshl_add_u64 v[36:37], v[14:15], 0, v[36:37]
	v_add_u32_e32 v20, s8, v50
	global_store_dwordx4 v[36:37], v[16:19], off
	v_add_u32_e32 v36, s8, v51
	v_ashrrev_i32_e32 v37, 31, v36
	v_cvt_pk_bf16_f32 v16, v23, v21
	v_ashrrev_i32_e32 v21, 31, v20
	v_lshlrev_b64 v[20:21], 11, v[20:21]
	v_cvt_pk_bf16_f32 v17, v25, v27
	v_cvt_pk_bf16_f32 v18, v29, v31
	v_cvt_pk_bf16_f32 v19, v33, v35
	v_lshl_add_u64 v[20:21], v[14:15], 0, v[20:21]
	global_store_dwordx4 v[20:21], v[16:19], off
	ds_read2_b32 v[20:21], v49 offset0:81 offset1:89
	ds_read2_b32 v[22:23], v49 offset0:16 offset1:24
	ds_read2_b32 v[24:25], v49 offset0:146 offset1:154
	ds_read2_b32 v[26:27], v49 offset0:211 offset1:219
	ds_read2_b32 v[28:29], v8 offset0:20 offset1:28
	ds_read2_b32 v[30:31], v8 offset0:85 offset1:93
	ds_read2_b32 v[32:33], v8 offset0:150 offset1:158
	ds_read2_b32 v[34:35], v8 offset0:215 offset1:223
	v_lshlrev_b64 v[36:37], 11, v[36:37]
	s_waitcnt lgkmcnt(6)
	v_cvt_pk_bf16_f32 v16, v22, v20
	s_waitcnt lgkmcnt(4)
	v_cvt_pk_bf16_f32 v17, v24, v26
	s_waitcnt lgkmcnt(2)
	v_cvt_pk_bf16_f32 v18, v28, v30
	s_waitcnt lgkmcnt(0)
	v_cvt_pk_bf16_f32 v19, v32, v34
	v_lshl_add_u64 v[36:37], v[14:15], 0, v[36:37]
	v_add_u32_e32 v20, s8, v52
	global_store_dwordx4 v[36:37], v[16:19], off
	v_add_u32_e32 v36, s8, v53
	v_ashrrev_i32_e32 v37, 31, v36
	v_cvt_pk_bf16_f32 v16, v23, v21
	v_ashrrev_i32_e32 v21, 31, v20
	v_lshlrev_b64 v[20:21], 11, v[20:21]
	v_cvt_pk_bf16_f32 v17, v25, v27
	v_cvt_pk_bf16_f32 v18, v29, v31
	v_cvt_pk_bf16_f32 v19, v33, v35
	v_lshl_add_u64 v[20:21], v[14:15], 0, v[20:21]
	global_store_dwordx4 v[20:21], v[16:19], off
	ds_read2_b32 v[20:21], v49 offset0:32 offset1:40
	ds_read2_b32 v[22:23], v49 offset0:97 offset1:105
	ds_read2_b32 v[24:25], v49 offset0:162 offset1:170
	ds_read2_b32 v[26:27], v49 offset0:227 offset1:235
	ds_read2_b32 v[28:29], v8 offset0:36 offset1:44
	ds_read2_b32 v[30:31], v8 offset0:101 offset1:109
	ds_read2_b32 v[32:33], v8 offset0:166 offset1:174
	ds_read2_b32 v[34:35], v8 offset0:231 offset1:239
	v_lshlrev_b64 v[36:37], 11, v[36:37]
	s_waitcnt lgkmcnt(6)
	v_cvt_pk_bf16_f32 v16, v20, v22
	s_waitcnt lgkmcnt(4)
	v_cvt_pk_bf16_f32 v17, v24, v26
	s_waitcnt lgkmcnt(2)
	v_cvt_pk_bf16_f32 v18, v28, v30
	s_waitcnt lgkmcnt(0)
	v_cvt_pk_bf16_f32 v19, v32, v34
	v_lshl_add_u64 v[36:37], v[14:15], 0, v[36:37]
	v_add_u32_e32 v20, s8, v54
	global_store_dwordx4 v[36:37], v[16:19], off
	v_add_u32_e32 v36, s8, v55
	v_ashrrev_i32_e32 v37, 31, v36
	v_cvt_pk_bf16_f32 v16, v21, v23
	v_ashrrev_i32_e32 v21, 31, v20
	v_lshlrev_b64 v[20:21], 11, v[20:21]
	v_cvt_pk_bf16_f32 v17, v25, v27
	v_cvt_pk_bf16_f32 v18, v29, v31
	v_cvt_pk_bf16_f32 v19, v33, v35
	v_lshl_add_u64 v[20:21], v[14:15], 0, v[20:21]
	global_store_dwordx4 v[20:21], v[16:19], off
	ds_read2_b32 v[20:21], v49 offset0:48 offset1:56
	ds_read2_b32 v[22:23], v49 offset0:113 offset1:121
	ds_read2_b32 v[24:25], v49 offset0:178 offset1:186
	ds_read2_b32 v[26:27], v49 offset0:243 offset1:251
	ds_read2_b32 v[28:29], v8 offset0:52 offset1:60
	ds_read2_b32 v[30:31], v8 offset0:117 offset1:125
	ds_read2_b32 v[32:33], v8 offset0:182 offset1:190
	ds_read2_b32 v[34:35], v8 offset0:247 offset1:255
	v_lshlrev_b64 v[36:37], 11, v[36:37]
	s_waitcnt lgkmcnt(6)
	v_cvt_pk_bf16_f32 v16, v20, v22
	s_waitcnt lgkmcnt(4)
	v_cvt_pk_bf16_f32 v17, v24, v26
	s_waitcnt lgkmcnt(2)
	v_cvt_pk_bf16_f32 v18, v28, v30
	s_waitcnt lgkmcnt(0)
	v_cvt_pk_bf16_f32 v19, v32, v34
	v_lshl_add_u64 v[36:37], v[14:15], 0, v[36:37]
	v_add_u32_e32 v20, s8, v56
	global_store_dwordx4 v[36:37], v[16:19], off
	s_mov_b64 s[8:9], 0
	s_nop 0
	v_cvt_pk_bf16_f32 v16, v21, v23
	v_ashrrev_i32_e32 v21, 31, v20
	v_lshlrev_b64 v[20:21], 11, v[20:21]
	v_cvt_pk_bf16_f32 v17, v25, v27
	v_cvt_pk_bf16_f32 v18, v29, v31
	v_cvt_pk_bf16_f32 v19, v33, v35
	v_lshl_add_u64 v[14:15], v[14:15], 0, v[20:21]
	global_store_dwordx4 v[14:15], v[16:19], off

.LBB0_224:
	v_lshl_add_u64 v[30:31], v[28:29], 0, s[8:9]
	global_load_dwordx4 v[30:33], v[30:31], off nt
	v_lshl_add_u64 v[194:195], v[26:27], 0, s[8:9]
	global_load_dwordx4 v[194:197], v[194:195], off nt
	v_lshl_add_u64 v[200:201], v[24:25], 0, s[8:9]
	global_load_dwordx4 v[200:203], v[200:201], off nt
	v_lshl_add_u64 v[210:211], v[22:23], 0, s[8:9]
	global_load_dwordx4 v[210:213], v[210:211], off nt
	v_lshl_add_u64 v[216:217], v[20:21], 0, s[8:9]
	global_load_dwordx4 v[216:219], v[216:217], off nt
	v_lshl_add_u64 v[222:223], v[18:19], 0, s[8:9]
	global_load_dwordx4 v[222:225], v[222:223], off nt
	v_lshl_add_u64 v[230:231], v[16:17], 0, s[8:9]
	global_load_dwordx4 v[230:233], v[230:231], off nt
	v_lshl_add_u64 v[188:189], v[14:15], 0, s[8:9]
	global_load_dwordx4 v[188:191], v[188:189], off nt
	s_waitcnt vmcnt(7)
	v_add_u32_e32 v34, 0x410, v8
	ds_write2_b32 v8, v30, v31 offset1:1
	ds_write2_b32 v8, v32, v33 offset0:2 offset1:3
	s_waitcnt vmcnt(6)
	ds_write2_b32 v34, v194, v195 offset1:1
	v_add_u32_e32 v194, 0x418, v8
	ds_write2_b32 v194, v196, v197 offset1:1
	s_waitcnt vmcnt(5)
	v_add_u32_e32 v204, 0x820, v8
	ds_write2_b32 v204, v200, v201 offset1:1
	v_add_u32_e32 v200, 0x828, v8
	ds_write2_b32 v200, v202, v203 offset1:1
	s_waitcnt vmcnt(4)
	v_add_u32_e32 v214, 0xc30, v8
	ds_write2_b32 v214, v210, v211 offset1:1
	v_add_u32_e32 v210, 0xc38, v8
	ds_write2_b32 v210, v212, v213 offset1:1
	s_waitcnt vmcnt(3)
	v_add_u32_e32 v220, 0x1040, v8
	ds_write2_b32 v220, v216, v217 offset1:1
	v_add_u32_e32 v216, 0x1048, v8
	ds_write2_b32 v216, v218, v219 offset1:1
	s_waitcnt vmcnt(2)
	v_add_u32_e32 v226, 0x1450, v8
	ds_write2_b32 v226, v222, v223 offset1:1
	v_add_u32_e32 v222, 0x1458, v8
	ds_write2_b32 v222, v224, v225 offset1:1
	s_waitcnt vmcnt(1)
	v_add_u32_e32 v234, 0x1860, v8
	ds_write2_b32 v234, v230, v231 offset1:1
	v_add_u32_e32 v230, 0x1868, v8
	ds_write2_b32 v230, v232, v233 offset1:1
	s_waitcnt vmcnt(0)
	s_add_u32 s8, s8, 0x20000
	v_add_u32_e32 v192, 0x1c70, v8
	s_addc_u32 s9, s9, 0
	s_cmp_lg_u32 s8, 0x40000
	ds_write2_b32 v192, v188, v189 offset1:1
	v_add_u32_e32 v188, 0x1c78, v8
	v_add_u32_e32 v8, 0x2080, v8
	ds_write2_b32 v188, v190, v191 offset1:1
	s_cbranch_scc1 .LBB0_224
	v_add_u32_e32 v8, 0x400, v49
	s_lshl_b32 s8, s21, 6
	s_lshl_b32 s9, s21, 2
	ds_read2_b32 v[20:21], v49 offset0:65 offset1:73
	ds_read2_b32 v[22:23], v49 offset1:8
	ds_read2_b32 v[24:25], v49 offset0:130 offset1:138
	ds_read2_b32 v[26:27], v49 offset0:195 offset1:203
	ds_read2_b32 v[28:29], v8 offset0:4 offset1:12
	ds_read2_b32 v[30:31], v8 offset0:69 offset1:77
	ds_read2_b32 v[32:33], v8 offset0:134 offset1:142
	ds_read2_b32 v[34:35], v8 offset0:199 offset1:207
	s_and_b32 s8, s8, 0x3c0
	s_and_b32 s14, s9, 0xc0
	s_addk_i32 s9, 0xe000
	s_and_b32 s9, s9, 0xffffff00
	v_add_u32_e32 v36, s8, v48
	s_or_b32 s82, s9, s14
	v_ashrrev_i32_e32 v37, 31, v36
	v_lshl_add_u64 v[14:15], s[82:83], 1, v[4:5]
	v_lshlrev_b64 v[36:37], 11, v[36:37]
	s_waitcnt lgkmcnt(6)
	v_cvt_pk_bf16_f32 v16, v22, v20
	s_waitcnt lgkmcnt(4)
	v_cvt_pk_bf16_f32 v17, v24, v26
	s_waitcnt lgkmcnt(2)
	v_cvt_pk_bf16_f32 v18, v28, v30
	s_waitcnt lgkmcnt(0)
	v_cvt_pk_bf16_f32 v19, v32, v34
	v_lshl_add_u64 v[36:37], v[14:15], 0, v[36:37]
	v_add_u32_e32 v20, s8, v50
	global_store_dwordx4 v[36:37], v[16:19], off
	v_add_u32_e32 v36, s8, v51
	v_ashrrev_i32_e32 v37, 31, v36
	v_cvt_pk_bf16_f32 v16, v23, v21
	v_ashrrev_i32_e32 v21, 31, v20
	v_lshlrev_b64 v[20:21], 11, v[20:21]
	v_cvt_pk_bf16_f32 v17, v25, v27
	v_cvt_pk_bf16_f32 v18, v29, v31
	v_cvt_pk_bf16_f32 v19, v33, v35
	v_lshl_add_u64 v[20:21], v[14:15], 0, v[20:21]
	global_store_dwordx4 v[20:21], v[16:19], off
	ds_read2_b32 v[20:21], v49 offset0:81 offset1:89
	ds_read2_b32 v[22:23], v49 offset0:16 offset1:24
	ds_read2_b32 v[24:25], v49 offset0:146 offset1:154
	ds_read2_b32 v[26:27], v49 offset0:211 offset1:219
	ds_read2_b32 v[28:29], v8 offset0:20 offset1:28
	ds_read2_b32 v[30:31], v8 offset0:85 offset1:93
	ds_read2_b32 v[32:33], v8 offset0:150 offset1:158
	ds_read2_b32 v[34:35], v8 offset0:215 offset1:223
	v_lshlrev_b64 v[36:37], 11, v[36:37]
	s_waitcnt lgkmcnt(6)
	v_cvt_pk_bf16_f32 v16, v22, v20
	s_waitcnt lgkmcnt(4)
	v_cvt_pk_bf16_f32 v17, v24, v26
	s_waitcnt lgkmcnt(2)
	v_cvt_pk_bf16_f32 v18, v28, v30
	s_waitcnt lgkmcnt(0)
	v_cvt_pk_bf16_f32 v19, v32, v34
	v_lshl_add_u64 v[36:37], v[14:15], 0, v[36:37]
	v_add_u32_e32 v20, s8, v52
	global_store_dwordx4 v[36:37], v[16:19], off
	v_add_u32_e32 v36, s8, v53
	v_ashrrev_i32_e32 v37, 31, v36
	v_cvt_pk_bf16_f32 v16, v23, v21
	v_ashrrev_i32_e32 v21, 31, v20
	v_lshlrev_b64 v[20:21], 11, v[20:21]
	v_cvt_pk_bf16_f32 v17, v25, v27
	v_cvt_pk_bf16_f32 v18, v29, v31
	v_cvt_pk_bf16_f32 v19, v33, v35
	v_lshl_add_u64 v[20:21], v[14:15], 0, v[20:21]
	global_store_dwordx4 v[20:21], v[16:19], off
	ds_read2_b32 v[20:21], v49 offset0:32 offset1:40
	ds_read2_b32 v[22:23], v49 offset0:97 offset1:105
	ds_read2_b32 v[24:25], v49 offset0:162 offset1:170
	ds_read2_b32 v[26:27], v49 offset0:227 offset1:235
	ds_read2_b32 v[28:29], v8 offset0:36 offset1:44
	ds_read2_b32 v[30:31], v8 offset0:101 offset1:109
	ds_read2_b32 v[32:33], v8 offset0:166 offset1:174
	ds_read2_b32 v[34:35], v8 offset0:231 offset1:239
	v_lshlrev_b64 v[36:37], 11, v[36:37]
	s_waitcnt lgkmcnt(6)
	v_cvt_pk_bf16_f32 v16, v20, v22
	s_waitcnt lgkmcnt(4)
	v_cvt_pk_bf16_f32 v17, v24, v26
	s_waitcnt lgkmcnt(2)
	v_cvt_pk_bf16_f32 v18, v28, v30
	s_waitcnt lgkmcnt(0)
	v_cvt_pk_bf16_f32 v19, v32, v34
	v_lshl_add_u64 v[36:37], v[14:15], 0, v[36:37]
	v_add_u32_e32 v20, s8, v54
	global_store_dwordx4 v[36:37], v[16:19], off
	v_add_u32_e32 v36, s8, v55
	v_ashrrev_i32_e32 v37, 31, v36
	v_cvt_pk_bf16_f32 v16, v21, v23
	v_ashrrev_i32_e32 v21, 31, v20
	v_lshlrev_b64 v[20:21], 11, v[20:21]
	v_cvt_pk_bf16_f32 v17, v25, v27
	v_cvt_pk_bf16_f32 v18, v29, v31
	v_cvt_pk_bf16_f32 v19, v33, v35
	v_lshl_add_u64 v[20:21], v[14:15], 0, v[20:21]
	global_store_dwordx4 v[20:21], v[16:19], off
	ds_read2_b32 v[20:21], v49 offset0:48 offset1:56
	ds_read2_b32 v[22:23], v49 offset0:113 offset1:121
	ds_read2_b32 v[24:25], v49 offset0:178 offset1:186
	ds_read2_b32 v[26:27], v49 offset0:243 offset1:251
	ds_read2_b32 v[28:29], v8 offset0:52 offset1:60
	ds_read2_b32 v[30:31], v8 offset0:117 offset1:125
	ds_read2_b32 v[32:33], v8 offset0:182 offset1:190
	ds_read2_b32 v[34:35], v8 offset0:247 offset1:255
	v_lshlrev_b64 v[36:37], 11, v[36:37]
	s_waitcnt lgkmcnt(6)
	v_cvt_pk_bf16_f32 v16, v20, v22
	s_waitcnt lgkmcnt(4)
	v_cvt_pk_bf16_f32 v17, v24, v26
	s_waitcnt lgkmcnt(2)
	v_cvt_pk_bf16_f32 v18, v28, v30
	s_waitcnt lgkmcnt(0)
	v_cvt_pk_bf16_f32 v19, v32, v34
	v_lshl_add_u64 v[36:37], v[14:15], 0, v[36:37]
	v_add_u32_e32 v20, s8, v56
	global_store_dwordx4 v[36:37], v[16:19], off
	s_nop 1
	v_cvt_pk_bf16_f32 v16, v21, v23
	v_ashrrev_i32_e32 v21, 31, v20
	v_lshlrev_b64 v[20:21], 11, v[20:21]
	v_cvt_pk_bf16_f32 v17, v25, v27
	v_cvt_pk_bf16_f32 v18, v29, v31
	v_cvt_pk_bf16_f32 v19, v33, v35
	v_lshl_add_u64 v[14:15], v[14:15], 0, v[20:21]
	global_store_dwordx4 v[14:15], v[16:19], off

.LBB0_239:
	v_lshl_add_u64 v[30:31], v[28:29], 0, s[14:15]
	global_load_dwordx4 v[30:33], v[30:31], off nt
	v_lshl_add_u64 v[194:195], v[26:27], 0, s[14:15]
	global_load_dwordx4 v[194:197], v[194:195], off nt
	v_lshl_add_u64 v[200:201], v[24:25], 0, s[14:15]
	global_load_dwordx4 v[200:203], v[200:201], off nt
	v_lshl_add_u64 v[210:211], v[22:23], 0, s[14:15]
	global_load_dwordx4 v[210:213], v[210:211], off nt
	v_lshl_add_u64 v[216:217], v[20:21], 0, s[14:15]
	global_load_dwordx4 v[216:219], v[216:217], off nt
	v_lshl_add_u64 v[222:223], v[18:19], 0, s[14:15]
	global_load_dwordx4 v[222:225], v[222:223], off nt
	v_lshl_add_u64 v[230:231], v[16:17], 0, s[14:15]
	global_load_dwordx4 v[230:233], v[230:231], off nt
	v_lshl_add_u64 v[188:189], v[14:15], 0, s[14:15]
	global_load_dwordx4 v[188:191], v[188:189], off nt
	s_waitcnt vmcnt(7)
	v_add_u32_e32 v34, 0x410, v8
	ds_write2_b32 v8, v30, v31 offset1:1
	ds_write2_b32 v8, v32, v33 offset0:2 offset1:3
	s_waitcnt vmcnt(6)
	ds_write2_b32 v34, v194, v195 offset1:1
	v_add_u32_e32 v194, 0x418, v8
	ds_write2_b32 v194, v196, v197 offset1:1
	s_waitcnt vmcnt(5)
	v_add_u32_e32 v204, 0x820, v8
	ds_write2_b32 v204, v200, v201 offset1:1
	v_add_u32_e32 v200, 0x828, v8
	ds_write2_b32 v200, v202, v203 offset1:1
	s_waitcnt vmcnt(4)
	v_add_u32_e32 v214, 0xc30, v8
	ds_write2_b32 v214, v210, v211 offset1:1
	v_add_u32_e32 v210, 0xc38, v8
	ds_write2_b32 v210, v212, v213 offset1:1
	s_waitcnt vmcnt(3)
	v_add_u32_e32 v220, 0x1040, v8
	ds_write2_b32 v220, v216, v217 offset1:1
	v_add_u32_e32 v216, 0x1048, v8
	ds_write2_b32 v216, v218, v219 offset1:1
	s_waitcnt vmcnt(2)
	v_add_u32_e32 v226, 0x1450, v8
	ds_write2_b32 v226, v222, v223 offset1:1
	v_add_u32_e32 v222, 0x1458, v8
	ds_write2_b32 v222, v224, v225 offset1:1
	s_waitcnt vmcnt(1)
	v_add_u32_e32 v234, 0x1860, v8
	ds_write2_b32 v234, v230, v231 offset1:1
	v_add_u32_e32 v230, 0x1868, v8
	ds_write2_b32 v230, v232, v233 offset1:1
	s_waitcnt vmcnt(0)
	s_add_u32 s14, s14, 0xf8800
	v_add_u32_e32 v192, 0x1c70, v8
	s_addc_u32 s15, s15, 0
	s_cmp_lg_u32 s14, 0x1f1000
	ds_write2_b32 v192, v188, v189 offset1:1
	v_add_u32_e32 v188, 0x1c78, v8
	v_add_u32_e32 v8, 0x2080, v8
	ds_write2_b32 v188, v190, v191 offset1:1
	s_cbranch_scc1 .LBB0_239
	v_add_u32_e32 v8, 0x400, v49
	ds_read2_b32 v[20:21], v49 offset0:65 offset1:73
	ds_read2_b32 v[22:23], v49 offset1:8
	ds_read2_b32 v[24:25], v49 offset0:130 offset1:138
	ds_read2_b32 v[26:27], v49 offset0:195 offset1:203
	ds_read2_b32 v[28:29], v8 offset0:4 offset1:12
	ds_read2_b32 v[30:31], v8 offset0:69 offset1:77
	ds_read2_b32 v[32:33], v8 offset0:134 offset1:142
	ds_read2_b32 v[34:35], v8 offset0:199 offset1:207
	v_add_u32_e32 v36, s22, v48
	s_ashr_i32 s9, s8, 31
	v_ashrrev_i32_e32 v37, 31, v36
	v_lshl_add_u64 v[14:15], s[8:9], 1, v[6:7]
	v_lshlrev_b64 v[36:37], 11, v[36:37]
	s_waitcnt lgkmcnt(6)
	v_cvt_pk_bf16_f32 v16, v22, v20
	s_waitcnt lgkmcnt(4)
	v_cvt_pk_bf16_f32 v17, v24, v26
	s_waitcnt lgkmcnt(2)
	v_cvt_pk_bf16_f32 v18, v28, v30
	s_waitcnt lgkmcnt(0)
	v_cvt_pk_bf16_f32 v19, v32, v34
	v_lshl_add_u64 v[36:37], v[14:15], 0, v[36:37]
	v_add_u32_e32 v20, s22, v50
	global_store_dwordx4 v[36:37], v[16:19], off
	v_add_u32_e32 v36, s22, v51
	v_ashrrev_i32_e32 v37, 31, v36
	v_cvt_pk_bf16_f32 v16, v23, v21
	v_ashrrev_i32_e32 v21, 31, v20
	v_lshlrev_b64 v[20:21], 11, v[20:21]
	v_cvt_pk_bf16_f32 v17, v25, v27
	v_cvt_pk_bf16_f32 v18, v29, v31
	v_cvt_pk_bf16_f32 v19, v33, v35
	v_lshl_add_u64 v[20:21], v[14:15], 0, v[20:21]
	global_store_dwordx4 v[20:21], v[16:19], off
	ds_read2_b32 v[20:21], v49 offset0:81 offset1:89
	ds_read2_b32 v[22:23], v49 offset0:16 offset1:24
	ds_read2_b32 v[24:25], v49 offset0:146 offset1:154
	ds_read2_b32 v[26:27], v49 offset0:211 offset1:219
	ds_read2_b32 v[28:29], v8 offset0:20 offset1:28
	ds_read2_b32 v[30:31], v8 offset0:85 offset1:93
	ds_read2_b32 v[32:33], v8 offset0:150 offset1:158
	ds_read2_b32 v[34:35], v8 offset0:215 offset1:223
	v_lshlrev_b64 v[36:37], 11, v[36:37]
	s_waitcnt lgkmcnt(6)
	v_cvt_pk_bf16_f32 v16, v22, v20
	s_waitcnt lgkmcnt(4)
	v_cvt_pk_bf16_f32 v17, v24, v26
	s_waitcnt lgkmcnt(2)
	v_cvt_pk_bf16_f32 v18, v28, v30
	s_waitcnt lgkmcnt(0)
	v_cvt_pk_bf16_f32 v19, v32, v34
	v_lshl_add_u64 v[36:37], v[14:15], 0, v[36:37]
	v_add_u32_e32 v20, s22, v52
	global_store_dwordx4 v[36:37], v[16:19], off
	v_add_u32_e32 v36, s22, v53
	v_ashrrev_i32_e32 v37, 31, v36
	v_cvt_pk_bf16_f32 v16, v23, v21
	v_ashrrev_i32_e32 v21, 31, v20
	v_lshlrev_b64 v[20:21], 11, v[20:21]
	v_cvt_pk_bf16_f32 v17, v25, v27
	v_cvt_pk_bf16_f32 v18, v29, v31
	v_cvt_pk_bf16_f32 v19, v33, v35
	v_lshl_add_u64 v[20:21], v[14:15], 0, v[20:21]
	global_store_dwordx4 v[20:21], v[16:19], off
	ds_read2_b32 v[20:21], v49 offset0:32 offset1:40
	ds_read2_b32 v[22:23], v49 offset0:97 offset1:105
	ds_read2_b32 v[24:25], v49 offset0:162 offset1:170
	ds_read2_b32 v[26:27], v49 offset0:227 offset1:235
	ds_read2_b32 v[28:29], v8 offset0:36 offset1:44
	ds_read2_b32 v[30:31], v8 offset0:101 offset1:109
	ds_read2_b32 v[32:33], v8 offset0:166 offset1:174
	ds_read2_b32 v[34:35], v8 offset0:231 offset1:239
	v_lshlrev_b64 v[36:37], 11, v[36:37]
	s_waitcnt lgkmcnt(6)
	v_cvt_pk_bf16_f32 v16, v20, v22
	s_waitcnt lgkmcnt(4)
	v_cvt_pk_bf16_f32 v17, v24, v26
	s_waitcnt lgkmcnt(2)
	v_cvt_pk_bf16_f32 v18, v28, v30
	s_waitcnt lgkmcnt(0)
	v_cvt_pk_bf16_f32 v19, v32, v34
	v_lshl_add_u64 v[36:37], v[14:15], 0, v[36:37]
	v_add_u32_e32 v20, s22, v54
	global_store_dwordx4 v[36:37], v[16:19], off
	v_add_u32_e32 v36, s22, v55
	v_ashrrev_i32_e32 v37, 31, v36
	v_cvt_pk_bf16_f32 v16, v21, v23
	v_ashrrev_i32_e32 v21, 31, v20
	v_lshlrev_b64 v[20:21], 11, v[20:21]
	v_cvt_pk_bf16_f32 v17, v25, v27
	v_cvt_pk_bf16_f32 v18, v29, v31
	v_cvt_pk_bf16_f32 v19, v33, v35
	v_lshl_add_u64 v[20:21], v[14:15], 0, v[20:21]
	global_store_dwordx4 v[20:21], v[16:19], off
	ds_read2_b32 v[20:21], v49 offset0:48 offset1:56
	ds_read2_b32 v[22:23], v49 offset0:113 offset1:121
	ds_read2_b32 v[24:25], v49 offset0:178 offset1:186
	ds_read2_b32 v[26:27], v49 offset0:243 offset1:251
	ds_read2_b32 v[28:29], v8 offset0:52 offset1:60
	ds_read2_b32 v[30:31], v8 offset0:117 offset1:125
	ds_read2_b32 v[32:33], v8 offset0:182 offset1:190
	ds_read2_b32 v[34:35], v8 offset0:247 offset1:255
	v_lshlrev_b64 v[36:37], 11, v[36:37]
	s_waitcnt lgkmcnt(6)
	v_cvt_pk_bf16_f32 v16, v20, v22
	s_waitcnt lgkmcnt(4)
	v_cvt_pk_bf16_f32 v17, v24, v26
	s_waitcnt lgkmcnt(2)
	v_cvt_pk_bf16_f32 v18, v28, v30
	s_waitcnt lgkmcnt(0)
	v_cvt_pk_bf16_f32 v19, v32, v34
	v_lshl_add_u64 v[36:37], v[14:15], 0, v[36:37]
	v_add_u32_e32 v20, s22, v56
	global_store_dwordx4 v[36:37], v[16:19], off
	s_mov_b64 s[8:9], 0
	s_nop 0
	v_cvt_pk_bf16_f32 v16, v21, v23
	v_ashrrev_i32_e32 v21, 31, v20
	v_lshlrev_b64 v[20:21], 11, v[20:21]
	v_cvt_pk_bf16_f32 v17, v25, v27
	v_cvt_pk_bf16_f32 v18, v29, v31
	v_cvt_pk_bf16_f32 v19, v33, v35
	v_lshl_add_u64 v[14:15], v[14:15], 0, v[20:21]
	global_store_dwordx4 v[14:15], v[16:19], off

.LBB0_257:
	v_mov_b32_e32 v194, 0
	v_mov_b32_e32 v196, 0
	v_mov_b32_e32 v198, 0
	v_mov_b32_e32 v200, 0
	v_mov_b32_e32 v202, 0
	v_mov_b32_e32 v204, 0
	v_mov_b32_e32 v206, 0
	v_mov_b32_e32 v210, 0
	s_and_saveexec_b64 s[16:17], vcc
	v_lshl_add_u64 v[194:195], v[44:45], 0, s[14:15]
	v_lshl_add_u64 v[196:197], v[42:43], 0, s[14:15]
	v_lshl_add_u64 v[198:199], v[40:41], 0, s[14:15]
	v_lshl_add_u64 v[200:201], v[38:39], 0, s[14:15]
	v_lshl_add_u64 v[202:203], v[36:37], 0, s[14:15]
	v_lshl_add_u64 v[204:205], v[34:35], 0, s[14:15]
	v_lshl_add_u64 v[206:207], v[32:33], 0, s[14:15]
	v_lshl_add_u64 v[210:211], v[14:15], 0, s[14:15]
	global_load_dword v194, v[194:195], off nt
	global_load_dword v196, v[196:197], off nt
	global_load_dword v198, v[198:199], off nt
	global_load_dword v200, v[200:201], off nt
	global_load_dword v202, v[202:203], off nt
	global_load_dword v204, v[204:205], off nt
	global_load_dword v206, v[206:207], off nt
	global_load_dword v210, v[210:211], off nt
	s_or_b64 exec, exec, s[16:17]
	s_add_u32 s14, s14, 0x7c400
	s_addc_u32 s15, s15, 0
	s_cmp_lg_u32 s14, 0x1f1000
	s_waitcnt vmcnt(7)
	ds_write_b32 v8, v194
	s_waitcnt vmcnt(6)
	ds_write_b32 v8, v196 offset:264
	s_waitcnt vmcnt(5)
	ds_write_b32 v8, v198 offset:528
	s_waitcnt vmcnt(4)
	ds_write_b32 v8, v200 offset:792
	s_waitcnt vmcnt(3)
	ds_write_b32 v8, v202 offset:1056
	s_waitcnt vmcnt(2)
	ds_write_b32 v8, v204 offset:1320
	s_waitcnt vmcnt(1)
	ds_write_b32 v8, v206 offset:1584
	s_waitcnt vmcnt(0)
	ds_write_b32 v8, v210 offset:1848
	v_add_u32_e32 v8, 0x840, v8
	s_cbranch_scc1 .LBB0_257

.LBB0_288:
	v_mov_b32_e32 v194, 0
	v_mov_b32_e32 v196, 0
	v_mov_b32_e32 v198, 0
	v_mov_b32_e32 v200, 0
	v_mov_b32_e32 v202, 0
	v_mov_b32_e32 v204, 0
	v_mov_b32_e32 v206, 0
	v_mov_b32_e32 v210, 0
	s_and_saveexec_b64 s[14:15], vcc
	v_lshl_add_u64 v[194:195], v[30:31], 0, s[8:9]
	v_lshl_add_u64 v[196:197], v[28:29], 0, s[8:9]
	v_lshl_add_u64 v[198:199], v[26:27], 0, s[8:9]
	v_lshl_add_u64 v[200:201], v[24:25], 0, s[8:9]
	v_lshl_add_u64 v[202:203], v[22:23], 0, s[8:9]
	v_lshl_add_u64 v[204:205], v[20:21], 0, s[8:9]
	v_lshl_add_u64 v[206:207], v[18:19], 0, s[8:9]
	v_lshl_add_u64 v[210:211], v[16:17], 0, s[8:9]
	global_load_dword v194, v[194:195], off nt
	global_load_dword v196, v[196:197], off nt
	global_load_dword v198, v[198:199], off nt
	global_load_dword v200, v[200:201], off nt
	global_load_dword v202, v[202:203], off nt
	global_load_dword v204, v[204:205], off nt
	global_load_dword v206, v[206:207], off nt
	global_load_dword v210, v[210:211], off nt
	s_or_b64 exec, exec, s[14:15]
	s_add_u32 s8, s8, 0x7c400
	s_addc_u32 s9, s9, 0
	s_cmp_lg_u32 s8, 0x1f1000
	s_waitcnt vmcnt(7)
	ds_write_b32 v8, v194
	s_waitcnt vmcnt(6)
	ds_write_b32 v8, v196 offset:264
	s_waitcnt vmcnt(5)
	ds_write_b32 v8, v198 offset:528
	s_waitcnt vmcnt(4)
	ds_write_b32 v8, v200 offset:792
	s_waitcnt vmcnt(3)
	ds_write_b32 v8, v202 offset:1056
	s_waitcnt vmcnt(2)
	ds_write_b32 v8, v204 offset:1320
	s_waitcnt vmcnt(1)
	ds_write_b32 v8, v206 offset:1584
	s_waitcnt vmcnt(0)
	ds_write_b32 v8, v210 offset:1848
	v_add_u32_e32 v8, 0x840, v8
	s_cbranch_scc1 .LBB0_288
	s_branch .LBB0_215

.LBB0_950:
	s_or_b64 exec, exec, s[12:13]
	v_pk_mul_f32 v[6:7], v[40:41], v[40:41]
	v_pk_mul_f32 v[42:43], v[38:39], v[38:39]
	v_lshlrev_b32_e32 v0, 2, v238
	v_pk_mov_b32 v[44:45], v[42:43], v[6:7] op_sel:[1,0]
	v_mov_b32_e32 v43, v7
	v_pk_add_f32 v[6:7], v[44:45], v[42:43]
	v_pk_mul_f32 v[42:43], v[36:37], v[36:37]
	v_pk_mul_f32 v[44:45], v[34:35], v[34:35]
	v_mul_f32_e32 v2, v26, v26
	v_pk_mov_b32 v[46:47], v[44:45], v[42:43] op_sel:[1,0]
	v_mov_b32_e32 v45, v43
	v_pk_add_f32 v[42:43], v[46:47], v[44:45]
	v_mul_f32_e32 v44, v27, v27
	v_pk_add_f32 v[6:7], v[6:7], v[6:7] op_sel:[0,1] op_sel_hi:[1,0]
	v_pk_add_f32 v[42:43], v[42:43], v[42:43] op_sel:[0,1] op_sel_hi:[1,0]
	v_xor_b32_e32 v3, 0x80, v0
	v_mov_b32_e32 v7, v2
	v_mov_b32_e32 v43, v44
	v_mul_f32_e32 v2, v31, v31
	v_mul_f32_e32 v45, v28, v28
	v_pk_add_f32 v[6:7], v[6:7], v[42:43]
	v_pk_fma_f32 v[42:43], v[30:31], v[30:31], v[2:3] op_sel_hi:[1,1,0]
	v_mul_f32_e32 v2, v33, v33
	v_mul_f32_e32 v46, v29, v29
	v_mov_b32_e32 v43, v45
	v_pk_fma_f32 v[44:45], v[32:33], v[32:33], v[2:3] op_sel_hi:[1,1,0]
	v_xor_b32_e32 v8, 64, v0
	v_mov_b32_e32 v45, v46
	v_pk_add_f32 v[42:43], v[42:43], v[44:45]
	s_mov_b32 s16, 0xf800000
	v_pk_add_f32 v[6:7], v[6:7], v[42:43]
	s_load_dwordx2 s[10:11], s[28:29], 0xa0
	v_add_f32_e32 v2, v6, v7
	ds_bpermute_b32 v6, v8, v2
	v_lshlrev_b32_e32 v0, 2, v167
	v_ashrrev_i32_e32 v1, 31, v0
	s_waitcnt lgkmcnt(0)
	s_add_u32 s10, s10, s54
	s_addc_u32 s11, s11, s55
	v_add_f32_e32 v2, v2, v6
	ds_bpermute_b32 v6, v3, v2
	v_lshl_add_u64 v[4:5], v[0:1], 2, s[10:11]
	v_lshlrev_b64 v[0:1], 1, v[0:1]
	s_mov_b32 s17, 0x9048000
	s_mov_b64 s[18:19], 0x9048400
	s_waitcnt lgkmcnt(0)
	v_add_f32_e32 v2, v2, v6
	v_fmamk_f32 v2, v2, 0x3c800000, v236
	v_cmp_gt_f32_e32 vcc, s16, v2
	v_mul_f32_e32 v6, 0x4f800000, v2
	s_mov_b32 s92, 0xf800000
	v_cndmask_b32_e32 v2, v2, v6, vcc
	v_sqrt_f32_e32 v6, v2
	s_nop 0
	v_add_u32_e32 v7, -1, v6
	v_fma_f32 v42, -v7, v6, v2
	v_cmp_ge_f32_e64 s[12:13], 0, v42
	v_add_u32_e32 v42, 1, v6
	s_nop 0
	v_cndmask_b32_e64 v7, v6, v7, s[12:13]
	v_fma_f32 v6, -v42, v6, v2
	v_cmp_lt_f32_e64 s[12:13], 0, v6
	s_nop 1
	v_cndmask_b32_e64 v6, v7, v42, s[12:13]
	v_mul_f32_e32 v7, 0x37800000, v6
	v_cndmask_b32_e32 v6, v6, v7, vcc
	v_cmp_class_f32_e32 vcc, v2, v237
	s_nop 1
	v_cndmask_b32_e32 v2, v6, v2, vcc
	v_div_scale_f32 v6, s[10:11], v2, v2, 1.0
	v_rcp_f32_e32 v7, v6
	s_nop 0
	v_fma_f32 v42, -v6, v7, 1.0
	v_fmac_f32_e32 v7, v42, v7
	v_div_scale_f32 v42, vcc, 1.0, v2, 1.0
	v_mul_f32_e32 v43, v42, v7
	v_fma_f32 v44, -v6, v43, v42
	v_fmac_f32_e32 v43, v44, v7
	v_fma_f32 v6, -v6, v43, v42
	v_div_fmas_f32 v6, v6, v7, v43
	v_div_fixup_f32 v2, v6, v2, 1.0
	v_lshlrev_b64 v[6:7], 11, v[130:131]
	v_lshl_add_u64 v[6:7], s[52:53], 0, v[6:7]
	v_lshl_add_u64 v[6:7], v[6:7], 0, s[82:83]
	v_lshl_add_u64 v[42:43], v[6:7], 0, v[0:1]
	v_add_co_u32_e32 v46, vcc, s17, v42
	v_lshl_add_u64 v[6:7], v[42:43], 0, s[18:19]
	s_nop 0
	v_addc_co_u32_e32 v47, vcc, 0, v43, vcc
	global_load_dwordx2 v[48:49], v[46:47], off offset:1024
	global_load_dwordx4 v[42:45], v[4:5], off
	global_load_dwordx2 v[210:211], v[6:7], off offset:32
	global_load_dwordx4 v[212:215], v[4:5], off offset:64
	global_load_dwordx2 v[216:217], v[6:7], off offset:64
	global_load_dwordx4 v[218:221], v[4:5], off offset:128
	global_load_dwordx2 v[222:223], v[6:7], off offset:96
	global_load_dwordx4 v[224:227], v[4:5], off offset:192
	v_pk_mul_f32 v[38:39], v[38:39], v[2:3] op_sel_hi:[1,0]
	v_pk_mul_f32 v[40:41], v[40:41], v[2:3] op_sel_hi:[1,0]
	v_pk_mul_f32 v[34:35], v[34:35], v[2:3] op_sel_hi:[1,0]
	v_pk_mul_f32 v[36:37], v[36:37], v[2:3] op_sel_hi:[1,0]
	v_pk_mul_f32 v[30:31], v[30:31], v[2:3] op_sel_hi:[1,0]
	v_pk_mul_f32 v[32:33], v[32:33], v[2:3] op_sel_hi:[1,0]
	v_pk_mul_f32 v[26:27], v[26:27], v[2:3] op_sel_hi:[1,0]
	v_pk_mul_f32 v[28:29], v[28:29], v[2:3] op_sel_hi:[1,0]
	v_mul_f32_e32 v2, v10, v10
	s_waitcnt vmcnt(0)
	v_pk_mul_f32 v[38:39], v[42:43], v[38:39]
	v_lshlrev_b32_e32 v42, 16, v48
	v_and_b32_e32 v43, 0xffff0000, v48
	v_pk_mul_f32 v[38:39], v[38:39], v[42:43]
	v_pk_mul_f32 v[40:41], v[44:45], v[40:41]
	v_lshlrev_b32_e32 v42, 16, v49
	v_and_b32_e32 v43, 0xffff0000, v49
	v_pk_mul_f32 v[40:41], v[40:41], v[42:43]
	v_cvt_pk_bf16_f32 v38, v38, v39
	v_cvt_pk_bf16_f32 v39, v40, v41
	global_store_dwordx2 v[46:47], v[38:39], off offset:1024
	v_mov_b64_e32 v[42:43], v[210:211]
	s_nop 0
	v_mov_b64_e32 v[38:39], v[212:213]
	v_mov_b64_e32 v[40:41], v[214:215]
	v_pk_mul_f32 v[34:35], v[38:39], v[34:35]
	v_lshlrev_b32_e32 v38, 16, v42
	v_and_b32_e32 v39, 0xffff0000, v42
	v_pk_mul_f32 v[34:35], v[34:35], v[38:39]
	v_pk_mul_f32 v[36:37], v[40:41], v[36:37]
	v_lshlrev_b32_e32 v38, 16, v43
	v_and_b32_e32 v39, 0xffff0000, v43
	v_pk_mul_f32 v[36:37], v[36:37], v[38:39]
	v_cvt_pk_bf16_f32 v34, v34, v35
	v_cvt_pk_bf16_f32 v35, v36, v37
	global_store_dwordx2 v[6:7], v[34:35], off offset:32
	v_mov_b64_e32 v[38:39], v[216:217]
	s_nop 0
	v_mov_b64_e32 v[34:35], v[218:219]
	v_mov_b64_e32 v[36:37], v[220:221]
	v_pk_mul_f32 v[30:31], v[30:31], v[34:35]
	v_lshlrev_b32_e32 v34, 16, v38
	v_and_b32_e32 v35, 0xffff0000, v38
	v_pk_mul_f32 v[30:31], v[30:31], v[34:35]
	v_pk_mul_f32 v[32:33], v[32:33], v[36:37]
	v_lshlrev_b32_e32 v34, 16, v39
	v_and_b32_e32 v35, 0xffff0000, v39
	v_pk_mul_f32 v[32:33], v[32:33], v[34:35]
	v_cvt_pk_bf16_f32 v30, v30, v31
	v_cvt_pk_bf16_f32 v31, v32, v33
	global_store_dwordx2 v[6:7], v[30:31], off offset:64
	v_mov_b64_e32 v[34:35], v[222:223]
	s_nop 0
	v_mov_b64_e32 v[30:31], v[224:225]
	v_mov_b64_e32 v[32:33], v[226:227]
	v_pk_mul_f32 v[26:27], v[26:27], v[30:31]
	v_lshlrev_b32_e32 v30, 16, v34
	v_and_b32_e32 v31, 0xffff0000, v34
	v_pk_mul_f32 v[26:27], v[26:27], v[30:31]
	v_pk_mul_f32 v[28:29], v[28:29], v[32:33]
	v_lshlrev_b32_e32 v30, 16, v35
	v_and_b32_e32 v31, 0xffff0000, v35
	v_pk_mul_f32 v[28:29], v[28:29], v[30:31]
	v_cvt_pk_bf16_f32 v26, v26, v27
	v_cvt_pk_bf16_f32 v27, v28, v29
	global_store_dwordx2 v[6:7], v[26:27], off offset:96
	v_pk_mul_f32 v[6:7], v[24:25], v[24:25]
	v_pk_mul_f32 v[26:27], v[22:23], v[22:23]
	s_nop 0
	v_pk_mov_b32 v[28:29], v[26:27], v[6:7] op_sel:[1,0]
	v_mov_b32_e32 v27, v7
	v_pk_add_f32 v[6:7], v[28:29], v[26:27]
	v_pk_mul_f32 v[26:27], v[20:21], v[20:21]
	v_pk_mul_f32 v[28:29], v[18:19], v[18:19]
	v_pk_add_f32 v[6:7], v[6:7], v[6:7] op_sel:[0,1] op_sel_hi:[1,0]
	v_pk_mov_b32 v[30:31], v[28:29], v[26:27] op_sel:[1,0]
	v_mov_b32_e32 v29, v27
	v_pk_add_f32 v[26:27], v[30:31], v[28:29]
	v_mul_f32_e32 v28, v11, v11
	v_pk_add_f32 v[26:27], v[26:27], v[26:27] op_sel:[0,1] op_sel_hi:[1,0]
	v_mov_b32_e32 v7, v2
	v_mov_b32_e32 v27, v28
	v_mul_f32_e32 v2, v15, v15
	v_mul_f32_e32 v29, v12, v12
	v_pk_add_f32 v[6:7], v[6:7], v[26:27]
	v_pk_fma_f32 v[26:27], v[14:15], v[14:15], v[2:3] op_sel_hi:[1,1,0]
	v_mul_f32_e32 v2, v17, v17
	v_mul_f32_e32 v30, v13, v13
	v_mov_b32_e32 v27, v29
	v_pk_fma_f32 v[28:29], v[16:17], v[16:17], v[2:3] op_sel_hi:[1,1,0]
	s_nop 0
	v_mov_b32_e32 v29, v30
	v_pk_add_f32 v[26:27], v[26:27], v[28:29]
	s_nop 0
	v_pk_add_f32 v[6:7], v[6:7], v[26:27]
	s_nop 0
	v_add_f32_e32 v2, v6, v7
	ds_bpermute_b32 v6, v8, v2
	s_waitcnt lgkmcnt(0)
	v_add_f32_e32 v2, v2, v6
	ds_bpermute_b32 v3, v3, v2
	s_waitcnt lgkmcnt(0)
	v_add_f32_e32 v2, v2, v3
	v_fmamk_f32 v2, v2, 0x3c800000, v236
	v_cmp_gt_f32_e32 vcc, s16, v2
	v_mul_f32_e32 v3, 0x4f800000, v2
	s_nop 0
	v_cndmask_b32_e32 v2, v2, v3, vcc
	v_sqrt_f32_e32 v3, v2
	s_nop 0
	v_add_u32_e32 v6, -1, v3
	v_fma_f32 v7, -v6, v3, v2
	v_cmp_ge_f32_e64 s[12:13], 0, v7
	v_add_u32_e32 v7, 1, v3
	s_nop 0
	v_cndmask_b32_e64 v6, v3, v6, s[12:13]
	v_fma_f32 v3, -v7, v3, v2
	v_cmp_lt_f32_e64 s[12:13], 0, v3
	s_nop 1
	v_cndmask_b32_e64 v3, v6, v7, s[12:13]
	v_mul_f32_e32 v6, 0x37800000, v3
	v_cndmask_b32_e32 v3, v3, v6, vcc
	v_cmp_class_f32_e32 vcc, v2, v237
	s_mov_b64 s[12:13], 0
	s_nop 0
	v_cndmask_b32_e32 v2, v3, v2, vcc
	v_div_scale_f32 v3, s[10:11], v2, v2, 1.0
	v_rcp_f32_e32 v6, v3
	s_nop 0
	v_fma_f32 v7, -v3, v6, 1.0
	v_fmac_f32_e32 v6, v7, v6
	v_div_scale_f32 v7, vcc, 1.0, v2, 1.0
	v_mul_f32_e32 v8, v7, v6
	v_fma_f32 v26, -v3, v8, v7
	v_fmac_f32_e32 v8, v26, v6
	v_fma_f32 v3, -v3, v8, v7
	v_div_fmas_f32 v3, v3, v6, v8
	v_div_fixup_f32 v6, v3, v2, 1.0
	v_or_b32_e32 v2, 16, v130
	v_ashrrev_i32_e32 v3, 31, v2
	v_lshlrev_b64 v[2:3], 11, v[2:3]
	v_lshl_add_u64 v[2:3], s[52:53], 0, v[2:3]
	v_lshl_add_u64 v[2:3], v[2:3], 0, s[82:83]
	v_lshl_add_u64 v[0:1], v[2:3], 0, v[0:1]
	v_add_co_u32_e32 v28, vcc, s17, v0
	v_lshl_add_u64 v[26:27], v[0:1], 0, s[18:19]
	s_nop 0
	v_addc_co_u32_e32 v29, vcc, 0, v1, vcc
	global_load_dwordx2 v[30:31], v[28:29], off offset:1024
	global_load_dwordx4 v[0:3], v[4:5], off
	global_load_dwordx2 v[210:211], v[26:27], off offset:32
	global_load_dwordx4 v[212:215], v[4:5], off offset:64
	global_load_dwordx2 v[216:217], v[26:27], off offset:64
	global_load_dwordx4 v[218:221], v[4:5], off offset:128
	global_load_dwordx2 v[222:223], v[26:27], off offset:96
	global_load_dwordx4 v[224:227], v[4:5], off offset:192
	v_pk_mul_f32 v[22:23], v[22:23], v[6:7] op_sel_hi:[1,0]
	v_pk_mul_f32 v[18:19], v[18:19], v[6:7] op_sel_hi:[1,0]
	v_pk_mul_f32 v[14:15], v[14:15], v[6:7] op_sel_hi:[1,0]
	s_waitcnt vmcnt(0)
	v_pk_mul_f32 v[0:1], v[0:1], v[22:23]
	v_lshlrev_b32_e32 v22, 16, v30
	v_and_b32_e32 v23, 0xffff0000, v30
	v_pk_mul_f32 v[0:1], v[0:1], v[22:23]
	v_pk_mul_f32 v[22:23], v[24:25], v[6:7] op_sel_hi:[1,0]
	v_cvt_pk_bf16_f32 v0, v0, v1
	v_pk_mul_f32 v[2:3], v[2:3], v[22:23]
	v_lshlrev_b32_e32 v22, 16, v31
	v_and_b32_e32 v23, 0xffff0000, v31
	v_pk_mul_f32 v[2:3], v[2:3], v[22:23]
	s_nop 0
	v_cvt_pk_bf16_f32 v1, v2, v3
	global_store_dwordx2 v[28:29], v[0:1], off offset:1024
	v_mov_b64_e32 v[22:23], v[210:211]
	s_nop 0
	v_mov_b64_e32 v[0:1], v[212:213]
	v_mov_b64_e32 v[2:3], v[214:215]
	v_pk_mul_f32 v[0:1], v[0:1], v[18:19]
	v_lshlrev_b32_e32 v18, 16, v22
	v_and_b32_e32 v19, 0xffff0000, v22
	v_pk_mul_f32 v[0:1], v[0:1], v[18:19]
	v_pk_mul_f32 v[18:19], v[20:21], v[6:7] op_sel_hi:[1,0]
	v_cvt_pk_bf16_f32 v0, v0, v1
	v_pk_mul_f32 v[2:3], v[2:3], v[18:19]
	v_lshlrev_b32_e32 v18, 16, v23
	v_and_b32_e32 v19, 0xffff0000, v23
	v_pk_mul_f32 v[2:3], v[2:3], v[18:19]
	s_nop 0
	v_cvt_pk_bf16_f32 v1, v2, v3
	global_store_dwordx2 v[26:27], v[0:1], off offset:32
	v_mov_b64_e32 v[18:19], v[216:217]
	s_nop 0
	v_mov_b64_e32 v[0:1], v[218:219]
	v_mov_b64_e32 v[2:3], v[220:221]
	v_pk_mul_f32 v[0:1], v[14:15], v[0:1]
	v_lshlrev_b32_e32 v14, 16, v18
	v_and_b32_e32 v15, 0xffff0000, v18
	v_pk_mul_f32 v[0:1], v[0:1], v[14:15]
	v_pk_mul_f32 v[14:15], v[16:17], v[6:7] op_sel_hi:[1,0]
	v_cvt_pk_bf16_f32 v0, v0, v1
	v_pk_mul_f32 v[2:3], v[14:15], v[2:3]
	v_lshlrev_b32_e32 v14, 16, v19
	v_and_b32_e32 v15, 0xffff0000, v19
	v_pk_mul_f32 v[2:3], v[2:3], v[14:15]
	s_nop 0
	v_cvt_pk_bf16_f32 v1, v2, v3
	global_store_dwordx2 v[26:27], v[0:1], off offset:64
	v_mov_b64_e32 v[14:15], v[222:223]
	s_nop 0
	v_mov_b64_e32 v[0:1], v[224:225]
	v_mov_b64_e32 v[2:3], v[226:227]
	v_pk_mul_f32 v[4:5], v[10:11], v[6:7] op_sel_hi:[1,0]
	v_pk_mul_f32 v[0:1], v[4:5], v[0:1]
	v_lshlrev_b32_e32 v4, 16, v14
	v_and_b32_e32 v5, 0xffff0000, v14
	v_pk_mul_f32 v[0:1], v[0:1], v[4:5]
	v_pk_mul_f32 v[4:5], v[12:13], v[6:7] op_sel_hi:[1,0]
	v_cvt_pk_bf16_f32 v0, v0, v1
	v_pk_mul_f32 v[2:3], v[4:5], v[2:3]
	v_lshlrev_b32_e32 v4, 16, v15
	v_and_b32_e32 v5, 0xffff0000, v15
	v_pk_mul_f32 v[2:3], v[2:3], v[4:5]
	s_nop 0
	v_cvt_pk_bf16_f32 v1, v2, v3
	global_store_dwordx2 v[26:27], v[0:1], off offset:96

.LBB0_967:
	s_or_b64 exec, exec, s[12:13]
	v_ashrrev_i32_e32 v8, 2, v238
	v_and_b32_e32 v34, -4, v8
	ds_bpermute_b32 v8, v115, v121
	v_lshlrev_b64 v[36:37], 11, v[130:131]
	v_ashrrev_i32_e32 v35, 31, v34
	v_lshl_add_u64 v[36:37], s[52:53], 0, v[36:37]
	v_lshl_add_u64 v[36:37], v[36:37], 0, s[82:83]
	s_waitcnt lgkmcnt(0)
	v_add_f32_e32 v8, v121, v8
	ds_bpermute_b32 v38, v114, v8
	v_lshlrev_b64 v[34:35], 1, v[34:35]
	v_lshl_add_u64 v[36:37], v[36:37], 0, v[34:35]
	s_mov_b64 s[16:17], 0x9048600
	s_mov_b32 s12, 0x9048000
	s_waitcnt lgkmcnt(0)
	v_add_f32_e32 v8, v8, v38
	v_div_scale_f32 v38, s[10:11], v8, v8, 1.0
	v_rcp_f32_e32 v39, v38
	s_nop 0
	v_fma_f32 v40, -v38, v39, 1.0
	v_fmac_f32_e32 v39, v40, v39
	v_div_scale_f32 v40, vcc, 1.0, v8, 1.0
	v_mul_f32_e32 v41, v40, v39
	v_fma_f32 v42, -v38, v41, v40
	v_fmac_f32_e32 v41, v42, v39
	v_fma_f32 v38, -v38, v41, v40
	v_div_fmas_f32 v38, v38, v39, v41
	v_div_fixup_f32 v8, v38, v8, 1.0
	v_lshl_add_u64 v[38:39], v[36:37], 0, s[16:17]
	v_add_co_u32_e32 v36, vcc, s12, v36
	v_pk_mul_f32 v[4:5], v[4:5], v[8:9] op_sel_hi:[1,0]
	s_nop 0
	v_addc_co_u32_e32 v37, vcc, 0, v37, vcc
	global_load_dwordx2 v[40:41], v[36:37], off offset:1536
	global_load_dwordx2 v[210:211], v[38:39], off offset:32
	global_load_dwordx2 v[212:213], v[38:39], off offset:64
	global_load_dwordx2 v[214:215], v[38:39], off offset:96
	v_pk_mul_f32 v[6:7], v[6:7], v[8:9] op_sel_hi:[1,0]
	s_waitcnt vmcnt(0)
	v_lshlrev_b32_e32 v42, 16, v40
	v_and_b32_e32 v43, 0xffff0000, v40
	v_lshlrev_b32_e32 v40, 16, v41
	v_and_b32_e32 v41, 0xffff0000, v41
	v_pk_mul_f32 v[4:5], v[4:5], v[42:43]
	v_pk_mul_f32 v[6:7], v[6:7], v[40:41]
	v_cvt_pk_bf16_f32 v4, v4, v5
	v_cvt_pk_bf16_f32 v5, v6, v7
	global_store_dwordx2 v[36:37], v[4:5], off offset:1536
	v_mov_b64_e32 v[4:5], v[210:211]
	v_pk_mul_f32 v[6:7], v[30:31], v[8:9] op_sel_hi:[1,0]
	v_lshlrev_b32_e32 v30, 16, v4
	v_and_b32_e32 v31, 0xffff0000, v4
	v_pk_mul_f32 v[6:7], v[6:7], v[30:31]
	v_pk_mul_f32 v[30:31], v[32:33], v[8:9] op_sel_hi:[1,0]
	v_lshlrev_b32_e32 v4, 16, v5
	v_and_b32_e32 v5, 0xffff0000, v5
	v_pk_mul_f32 v[4:5], v[30:31], v[4:5]
	v_cvt_pk_bf16_f32 v6, v6, v7
	v_cvt_pk_bf16_f32 v7, v4, v5
	v_mov_b64_e32 v[4:5], v[212:213]
	s_nop 0
	global_store_dwordx2 v[38:39], v[6:7], off offset:32
	v_pk_mul_f32 v[6:7], v[26:27], v[8:9] op_sel_hi:[1,0]
	v_lshlrev_b32_e32 v26, 16, v4
	v_and_b32_e32 v27, 0xffff0000, v4
	v_pk_mul_f32 v[6:7], v[6:7], v[26:27]
	v_pk_mul_f32 v[26:27], v[28:29], v[8:9] op_sel_hi:[1,0]
	v_lshlrev_b32_e32 v4, 16, v5
	v_and_b32_e32 v5, 0xffff0000, v5
	v_pk_mul_f32 v[4:5], v[26:27], v[4:5]
	v_cvt_pk_bf16_f32 v6, v6, v7
	v_cvt_pk_bf16_f32 v7, v4, v5
	v_mov_b64_e32 v[4:5], v[214:215]
	s_nop 0
	global_store_dwordx2 v[38:39], v[6:7], off offset:64
	v_pk_mul_f32 v[6:7], v[22:23], v[8:9] op_sel_hi:[1,0]
	v_lshlrev_b32_e32 v22, 16, v4
	v_and_b32_e32 v23, 0xffff0000, v4
	v_pk_mul_f32 v[6:7], v[6:7], v[22:23]
	v_pk_mul_f32 v[22:23], v[24:25], v[8:9] op_sel_hi:[1,0]
	v_lshlrev_b32_e32 v4, 16, v5
	v_and_b32_e32 v5, 0xffff0000, v5
	v_pk_mul_f32 v[4:5], v[22:23], v[4:5]
	v_cvt_pk_bf16_f32 v6, v6, v7
	v_cvt_pk_bf16_f32 v7, v4, v5
	global_store_dwordx2 v[38:39], v[6:7], off offset:96
	ds_bpermute_b32 v6, v115, v116
	v_or_b32_e32 v4, 16, v130
	v_ashrrev_i32_e32 v5, 31, v4
	v_lshlrev_b64 v[4:5], 11, v[4:5]
	v_lshl_add_u64 v[4:5], s[52:53], 0, v[4:5]
	s_waitcnt lgkmcnt(0)
	v_add_f32_e32 v6, v116, v6
	ds_bpermute_b32 v7, v114, v6
	v_lshl_add_u64 v[4:5], v[4:5], 0, s[82:83]
	s_waitcnt lgkmcnt(0)
	v_add_f32_e32 v6, v6, v7
	v_div_scale_f32 v7, s[10:11], v6, v6, 1.0
	v_rcp_f32_e32 v8, v7
	s_nop 0
	v_fma_f32 v22, -v7, v8, 1.0
	v_fmac_f32_e32 v8, v22, v8
	v_div_scale_f32 v22, vcc, 1.0, v6, 1.0
	v_mul_f32_e32 v23, v22, v8
	v_fma_f32 v24, -v7, v23, v22
	v_fmac_f32_e32 v23, v24, v8
	v_fma_f32 v7, -v7, v23, v22
	v_div_fmas_f32 v7, v7, v8, v23
	v_lshl_add_u64 v[22:23], v[4:5], 0, v[34:35]
	v_lshl_add_u64 v[4:5], v[22:23], 0, s[16:17]
	v_add_co_u32_e32 v22, vcc, s12, v22
	v_div_fixup_f32 v6, v7, v6, 1.0
	s_nop 0
	v_addc_co_u32_e32 v23, vcc, 0, v23, vcc
	global_load_dwordx2 v[24:25], v[22:23], off offset:1536
	global_load_dwordx2 v[210:211], v[4:5], off offset:32
	global_load_dwordx2 v[212:213], v[4:5], off offset:64
	global_load_dwordx2 v[214:215], v[4:5], off offset:96
	v_pk_mul_f32 v[18:19], v[18:19], v[6:7] op_sel_hi:[1,0]
	v_pk_mul_f32 v[20:21], v[20:21], v[6:7] op_sel_hi:[1,0]
	v_pk_mul_f32 v[14:15], v[14:15], v[6:7] op_sel_hi:[1,0]
	v_pk_mul_f32 v[16:17], v[16:17], v[6:7] op_sel_hi:[1,0]
	v_pk_mul_f32 v[10:11], v[10:11], v[6:7] op_sel_hi:[1,0]
	v_pk_mul_f32 v[12:13], v[12:13], v[6:7] op_sel_hi:[1,0]
	v_pk_mul_f32 v[0:1], v[0:1], v[6:7] op_sel_hi:[1,0]
	v_pk_mul_f32 v[2:3], v[2:3], v[6:7] op_sel_hi:[1,0]
	s_waitcnt vmcnt(0)
	v_lshlrev_b32_e32 v26, 16, v24
	v_and_b32_e32 v27, 0xffff0000, v24
	v_lshlrev_b32_e32 v24, 16, v25
	v_and_b32_e32 v25, 0xffff0000, v25
	v_pk_mul_f32 v[18:19], v[18:19], v[26:27]
	v_pk_mul_f32 v[20:21], v[20:21], v[24:25]
	v_cvt_pk_bf16_f32 v18, v18, v19
	v_cvt_pk_bf16_f32 v19, v20, v21
	global_store_dwordx2 v[22:23], v[18:19], off offset:1536
	v_mov_b64_e32 v[18:19], v[210:211]
	v_lshlrev_b32_e32 v20, 16, v18
	v_and_b32_e32 v21, 0xffff0000, v18
	v_lshlrev_b32_e32 v18, 16, v19
	v_and_b32_e32 v19, 0xffff0000, v19
	v_pk_mul_f32 v[14:15], v[14:15], v[20:21]
	v_pk_mul_f32 v[16:17], v[16:17], v[18:19]
	v_cvt_pk_bf16_f32 v14, v14, v15
	v_cvt_pk_bf16_f32 v15, v16, v17
	global_store_dwordx2 v[4:5], v[14:15], off offset:32
	v_mov_b64_e32 v[14:15], v[212:213]
	v_lshlrev_b32_e32 v16, 16, v14
	v_and_b32_e32 v17, 0xffff0000, v14
	v_lshlrev_b32_e32 v14, 16, v15
	v_and_b32_e32 v15, 0xffff0000, v15
	v_pk_mul_f32 v[10:11], v[10:11], v[16:17]
	v_pk_mul_f32 v[12:13], v[12:13], v[14:15]
	v_cvt_pk_bf16_f32 v10, v10, v11
	v_cvt_pk_bf16_f32 v11, v12, v13
	global_store_dwordx2 v[4:5], v[10:11], off offset:64
	v_mov_b64_e32 v[10:11], v[214:215]
	v_lshlrev_b32_e32 v12, 16, v10
	v_and_b32_e32 v13, 0xffff0000, v10
	v_lshlrev_b32_e32 v6, 16, v11
	v_and_b32_e32 v7, 0xffff0000, v11
	v_pk_mul_f32 v[0:1], v[0:1], v[12:13]
	v_pk_mul_f32 v[2:3], v[2:3], v[6:7]
	v_cvt_pk_bf16_f32 v0, v0, v1
	v_cvt_pk_bf16_f32 v1, v2, v3
	global_store_dwordx2 v[4:5], v[0:1], off offset:96

.LBB0_1045:
	s_or_b64 exec, exec, s[12:13]
	v_lshlrev_b64 v[2:3], 11, v[114:115]
	v_lshl_add_u64 v[2:3], s[52:53], 0, v[2:3]
	s_lshl_b32 s82, s85, 1
	v_lshl_add_u64 v[10:11], v[2:3], 0, s[82:83]
	ds_bpermute_b32 v2, v127, v133
	v_ashrrev_i32_e32 v0, 2, v238
	v_and_b32_e32 v0, -4, v0
	v_ashrrev_i32_e32 v1, 31, v0
	v_lshlrev_b64 v[0:1], 1, v[0:1]
	s_waitcnt lgkmcnt(0)
	v_add_f32_e32 v2, v133, v2
	ds_bpermute_b32 v3, v126, v2
	v_lshl_add_u64 v[10:11], v[10:11], 0, v[0:1]
	s_mov_b64 s[14:15], 0x9048600
	s_mov_b32 s12, 0x9048000
	v_readlane_b32 s56, v251, 4
	s_waitcnt lgkmcnt(0)
	v_add_f32_e32 v2, v2, v3
	v_div_scale_f32 v3, s[10:11], v2, v2, 1.0
	v_rcp_f32_e32 v8, v3
	s_mul_hi_i32 s57, s48, 0x3000
	s_mul_i32 s60, s48, 0x3000
	v_readlane_b32 s85, v254, 54
	v_fma_f32 v12, -v3, v8, 1.0
	v_fmac_f32_e32 v8, v12, v8
	v_div_scale_f32 v12, vcc, 1.0, v2, 1.0
	v_mul_f32_e32 v13, v12, v8
	v_fma_f32 v14, -v3, v13, v12
	v_fmac_f32_e32 v13, v14, v8
	v_fma_f32 v3, -v3, v13, v12
	v_div_fmas_f32 v3, v3, v8, v13
	v_lshl_add_u64 v[12:13], v[10:11], 0, s[14:15]
	v_add_co_u32_e32 v10, vcc, s12, v10
	v_div_fixup_f32 v2, v3, v2, 1.0
	s_nop 0
	v_addc_co_u32_e32 v11, vcc, 0, v11, vcc
	global_load_dwordx2 v[14:15], v[10:11], off offset:1536
	global_load_dwordx2 v[210:211], v[12:13], off offset:32
	global_load_dwordx2 v[212:213], v[12:13], off offset:64
	global_load_dwordx2 v[214:215], v[12:13], off offset:96
	v_pk_mul_f32 v[16:17], v[54:55], v[2:3] op_sel_hi:[1,0]
	s_waitcnt vmcnt(0)
	v_lshlrev_b32_e32 v18, 16, v14
	v_and_b32_e32 v19, 0xffff0000, v14
	v_pk_mul_f32 v[16:17], v[16:17], v[18:19]
	v_pk_mul_f32 v[18:19], v[56:57], v[2:3] op_sel_hi:[1,0]
	v_lshlrev_b32_e32 v14, 16, v15
	v_and_b32_e32 v15, 0xffff0000, v15
	v_pk_mul_f32 v[14:15], v[18:19], v[14:15]
	v_cvt_pk_bf16_f32 v16, v16, v17
	v_cvt_pk_bf16_f32 v17, v14, v15
	global_store_dwordx2 v[10:11], v[16:17], off offset:1536
	v_mov_b64_e32 v[10:11], v[210:211]
	v_pk_mul_f32 v[14:15], v[38:39], v[2:3] op_sel_hi:[1,0]
	v_lshlrev_b32_e32 v16, 16, v10
	v_and_b32_e32 v17, 0xffff0000, v10
	v_pk_mul_f32 v[14:15], v[14:15], v[16:17]
	v_pk_mul_f32 v[16:17], v[40:41], v[2:3] op_sel_hi:[1,0]
	v_lshlrev_b32_e32 v10, 16, v11
	v_and_b32_e32 v11, 0xffff0000, v11
	v_pk_mul_f32 v[10:11], v[16:17], v[10:11]
	v_cvt_pk_bf16_f32 v14, v14, v15
	v_cvt_pk_bf16_f32 v15, v10, v11
	v_mov_b64_e32 v[10:11], v[212:213]
	v_lshlrev_b32_e32 v16, 16, v10
	global_store_dwordx2 v[12:13], v[14:15], off offset:32
	v_pk_mul_f32 v[14:15], v[34:35], v[2:3] op_sel_hi:[1,0]
	v_and_b32_e32 v17, 0xffff0000, v10
	v_pk_mul_f32 v[14:15], v[14:15], v[16:17]
	v_pk_mul_f32 v[16:17], v[36:37], v[2:3] op_sel_hi:[1,0]
	v_lshlrev_b32_e32 v10, 16, v11
	v_and_b32_e32 v11, 0xffff0000, v11
	v_pk_mul_f32 v[10:11], v[16:17], v[10:11]
	v_cvt_pk_bf16_f32 v14, v14, v15
	v_cvt_pk_bf16_f32 v15, v10, v11
	v_mov_b64_e32 v[10:11], v[214:215]
	v_lshlrev_b32_e32 v16, 16, v10
	global_store_dwordx2 v[12:13], v[14:15], off offset:64
	v_pk_mul_f32 v[14:15], v[30:31], v[2:3] op_sel_hi:[1,0]
	v_and_b32_e32 v17, 0xffff0000, v10
	v_pk_mul_f32 v[2:3], v[32:33], v[2:3] op_sel_hi:[1,0]
	v_lshlrev_b32_e32 v10, 16, v11
	v_and_b32_e32 v11, 0xffff0000, v11
	v_pk_mul_f32 v[2:3], v[2:3], v[10:11]
	v_pk_mul_f32 v[14:15], v[14:15], v[16:17]
	v_cvt_pk_bf16_f32 v11, v2, v3
	v_or_b32_e32 v2, 16, v114
	v_ashrrev_i32_e32 v3, 31, v2
	v_lshlrev_b64 v[2:3], 11, v[2:3]
	v_cvt_pk_bf16_f32 v10, v14, v15
	v_lshl_add_u64 v[2:3], s[52:53], 0, v[2:3]
	global_store_dwordx2 v[12:13], v[10:11], off offset:96
	v_lshl_add_u64 v[10:11], v[2:3], 0, s[82:83]
	ds_bpermute_b32 v2, v127, v132
	v_lshl_add_u64 v[10:11], v[10:11], 0, v[0:1]
	v_lshl_add_u64 v[0:1], v[10:11], 0, s[14:15]
	s_waitcnt lgkmcnt(0)
	v_add_f32_e32 v2, v132, v2
	ds_bpermute_b32 v3, v126, v2
	s_waitcnt lgkmcnt(0)
	v_add_f32_e32 v2, v2, v3
	v_div_scale_f32 v3, s[10:11], v2, v2, 1.0
	v_rcp_f32_e32 v8, v3
	s_nop 0
	v_fma_f32 v12, -v3, v8, 1.0
	v_fmac_f32_e32 v8, v12, v8
	v_div_scale_f32 v12, vcc, 1.0, v2, 1.0
	v_mul_f32_e32 v13, v12, v8
	v_fma_f32 v14, -v3, v13, v12
	v_fmac_f32_e32 v13, v14, v8
	v_fma_f32 v3, -v3, v13, v12
	v_div_fmas_f32 v3, v3, v8, v13
	v_add_co_u32_e32 v10, vcc, s12, v10
	v_div_fixup_f32 v2, v3, v2, 1.0
	s_nop 0
	v_addc_co_u32_e32 v11, vcc, 0, v11, vcc
	global_load_dwordx2 v[12:13], v[10:11], off offset:1536
	global_load_dwordx2 v[210:211], v[0:1], off offset:32
	global_load_dwordx2 v[212:213], v[0:1], off offset:64
	global_load_dwordx2 v[214:215], v[0:1], off offset:96
	v_pk_mul_f32 v[14:15], v[42:43], v[2:3] op_sel_hi:[1,0]
	v_pk_mul_f32 v[4:5], v[4:5], v[2:3] op_sel_hi:[1,0]
	s_mov_b64 s[12:13], 0
	s_waitcnt vmcnt(0)
	v_lshlrev_b32_e32 v16, 16, v12
	v_and_b32_e32 v17, 0xffff0000, v12
	v_pk_mul_f32 v[14:15], v[14:15], v[16:17]
	v_pk_mul_f32 v[16:17], v[44:45], v[2:3] op_sel_hi:[1,0]
	v_lshlrev_b32_e32 v12, 16, v13
	v_and_b32_e32 v13, 0xffff0000, v13
	v_pk_mul_f32 v[12:13], v[16:17], v[12:13]
	v_cvt_pk_bf16_f32 v14, v14, v15
	v_cvt_pk_bf16_f32 v15, v12, v13
	global_store_dwordx2 v[10:11], v[14:15], off offset:1536
	v_mov_b64_e32 v[10:11], v[210:211]
	v_pk_mul_f32 v[12:13], v[26:27], v[2:3] op_sel_hi:[1,0]
	v_lshlrev_b32_e32 v14, 16, v10
	v_and_b32_e32 v15, 0xffff0000, v10
	v_pk_mul_f32 v[12:13], v[12:13], v[14:15]
	v_pk_mul_f32 v[14:15], v[28:29], v[2:3] op_sel_hi:[1,0]
	v_lshlrev_b32_e32 v10, 16, v11
	v_and_b32_e32 v11, 0xffff0000, v11
	v_pk_mul_f32 v[10:11], v[14:15], v[10:11]
	v_cvt_pk_bf16_f32 v12, v12, v13
	v_cvt_pk_bf16_f32 v13, v10, v11
	v_mov_b64_e32 v[10:11], v[212:213]
	v_lshlrev_b32_e32 v14, 16, v10
	global_store_dwordx2 v[0:1], v[12:13], off offset:32
	v_pk_mul_f32 v[12:13], v[22:23], v[2:3] op_sel_hi:[1,0]
	v_and_b32_e32 v15, 0xffff0000, v10
	v_pk_mul_f32 v[12:13], v[12:13], v[14:15]
	v_pk_mul_f32 v[14:15], v[24:25], v[2:3] op_sel_hi:[1,0]
	v_lshlrev_b32_e32 v10, 16, v11
	v_and_b32_e32 v11, 0xffff0000, v11
	v_pk_mul_f32 v[10:11], v[14:15], v[10:11]
	v_cvt_pk_bf16_f32 v12, v12, v13
	v_cvt_pk_bf16_f32 v13, v10, v11
	v_mov_b64_e32 v[10:11], v[214:215]
	v_pk_mul_f32 v[2:3], v[6:7], v[2:3] op_sel_hi:[1,0]
	global_store_dwordx2 v[0:1], v[12:13], off offset:64
	v_lshlrev_b32_e32 v12, 16, v10
	v_and_b32_e32 v13, 0xffff0000, v10
	v_lshlrev_b32_e32 v6, 16, v11
	v_and_b32_e32 v7, 0xffff0000, v11
	v_pk_mul_f32 v[4:5], v[4:5], v[12:13]
	v_pk_mul_f32 v[2:3], v[2:3], v[6:7]
	v_cvt_pk_bf16_f32 v4, v4, v5
	v_cvt_pk_bf16_f32 v5, v2, v3
	global_store_dwordx2 v[0:1], v[4:5], off offset:96

.LBB0_1076:
	s_or_b64 exec, exec, s[12:13]
	v_pk_mul_f32 v[6:7], v[20:21], v[20:21]
	v_pk_mul_f32 v[22:23], v[18:19], v[18:19]
	v_lshlrev_b32_e32 v0, 2, v238
	v_pk_mov_b32 v[24:25], v[22:23], v[6:7] op_sel:[1,0]
	v_mov_b32_e32 v23, v7
	v_pk_add_f32 v[6:7], v[24:25], v[22:23]
	v_pk_mul_f32 v[22:23], v[44:45], v[44:45]
	v_pk_mul_f32 v[24:25], v[42:43], v[42:43]
	v_mul_f32_e32 v2, v10, v10
	v_pk_mov_b32 v[26:27], v[24:25], v[22:23] op_sel:[1,0]
	v_mov_b32_e32 v25, v23
	v_pk_add_f32 v[22:23], v[26:27], v[24:25]
	v_mul_f32_e32 v24, v11, v11
	v_pk_add_f32 v[6:7], v[6:7], v[6:7] op_sel:[0,1] op_sel_hi:[1,0]
	v_pk_add_f32 v[22:23], v[22:23], v[22:23] op_sel:[0,1] op_sel_hi:[1,0]
	v_xor_b32_e32 v3, 0x80, v0
	v_mov_b32_e32 v7, v2
	v_mov_b32_e32 v23, v24
	v_mul_f32_e32 v2, v47, v47
	v_mul_f32_e32 v25, v12, v12
	v_pk_add_f32 v[6:7], v[6:7], v[22:23]
	v_pk_fma_f32 v[22:23], v[46:47], v[46:47], v[2:3] op_sel_hi:[1,1,0]
	v_mul_f32_e32 v2, v49, v49
	v_mul_f32_e32 v26, v13, v13
	v_mov_b32_e32 v23, v25
	v_pk_fma_f32 v[24:25], v[48:49], v[48:49], v[2:3] op_sel_hi:[1,1,0]
	v_xor_b32_e32 v8, 64, v0
	v_mov_b32_e32 v25, v26
	v_pk_add_f32 v[22:23], v[22:23], v[24:25]
	s_mov_b32 s14, 0xf800000
	v_pk_add_f32 v[6:7], v[6:7], v[22:23]
	s_load_dwordx2 s[10:11], s[28:29], 0xa0
	v_add_f32_e32 v2, v6, v7
	ds_bpermute_b32 v6, v8, v2
	v_lshlrev_b32_e32 v0, 2, v179
	v_ashrrev_i32_e32 v1, 31, v0
	s_waitcnt lgkmcnt(0)
	s_add_u32 s10, s10, s54
	s_addc_u32 s11, s11, s55
	v_add_f32_e32 v2, v2, v6
	ds_bpermute_b32 v6, v3, v2
	v_lshl_add_u64 v[4:5], v[0:1], 2, s[10:11]
	s_lshl_b32 s82, s18, 1
	v_lshlrev_b64 v[0:1], 1, v[0:1]
	s_mov_b32 s15, 0x9048000
	s_waitcnt lgkmcnt(0)
	v_add_f32_e32 v2, v2, v6
	v_fmamk_f32 v2, v2, 0x3c800000, v236
	v_cmp_gt_f32_e32 vcc, s14, v2
	v_mul_f32_e32 v6, 0x4f800000, v2
	s_mov_b64 s[16:17], 0x9048400
	v_cndmask_b32_e32 v2, v2, v6, vcc
	v_sqrt_f32_e32 v6, v2
	s_mov_b32 s92, 0xf800000
	v_add_u32_e32 v7, -1, v6
	v_fma_f32 v22, -v7, v6, v2
	v_cmp_ge_f32_e64 s[12:13], 0, v22
	v_add_u32_e32 v22, 1, v6
	s_nop 0
	v_cndmask_b32_e64 v7, v6, v7, s[12:13]
	v_fma_f32 v6, -v22, v6, v2
	v_cmp_lt_f32_e64 s[12:13], 0, v6
	s_nop 1
	v_cndmask_b32_e64 v6, v7, v22, s[12:13]
	v_mul_f32_e32 v7, 0x37800000, v6
	v_cndmask_b32_e32 v6, v6, v7, vcc
	v_cmp_class_f32_e32 vcc, v2, v237
	s_nop 1
	v_cndmask_b32_e32 v2, v6, v2, vcc
	v_div_scale_f32 v6, s[10:11], v2, v2, 1.0
	v_rcp_f32_e32 v7, v6
	s_nop 0
	v_fma_f32 v22, -v6, v7, 1.0
	v_fmac_f32_e32 v7, v22, v7
	v_div_scale_f32 v22, vcc, 1.0, v2, 1.0
	v_mul_f32_e32 v23, v22, v7
	v_fma_f32 v24, -v6, v23, v22
	v_fmac_f32_e32 v23, v24, v7
	v_fma_f32 v6, -v6, v23, v22
	v_div_fmas_f32 v6, v6, v7, v23
	v_div_fixup_f32 v2, v6, v2, 1.0
	v_lshlrev_b64 v[6:7], 11, v[142:143]
	v_lshl_add_u64 v[6:7], s[52:53], 0, v[6:7]
	v_lshl_add_u64 v[6:7], v[6:7], 0, s[82:83]
	v_lshl_add_u64 v[22:23], v[6:7], 0, v[0:1]
	v_add_co_u32_e32 v26, vcc, s15, v22
	v_lshl_add_u64 v[6:7], v[22:23], 0, s[16:17]
	s_nop 0
	v_addc_co_u32_e32 v27, vcc, 0, v23, vcc
	global_load_dwordx2 v[28:29], v[26:27], off offset:1024
	global_load_dwordx4 v[22:25], v[4:5], off
	global_load_dwordx2 v[210:211], v[6:7], off offset:32
	global_load_dwordx4 v[212:215], v[4:5], off offset:64
	global_load_dwordx2 v[216:217], v[6:7], off offset:64
	global_load_dwordx4 v[218:221], v[4:5], off offset:128
	global_load_dwordx2 v[222:223], v[6:7], off offset:96
	global_load_dwordx4 v[224:227], v[4:5], off offset:192
	v_pk_mul_f32 v[18:19], v[18:19], v[2:3] op_sel_hi:[1,0]
	v_pk_mul_f32 v[20:21], v[20:21], v[2:3] op_sel_hi:[1,0]
	v_pk_mul_f32 v[10:11], v[10:11], v[2:3] op_sel_hi:[1,0]
	v_pk_mul_f32 v[12:13], v[12:13], v[2:3] op_sel_hi:[1,0]
	s_waitcnt vmcnt(0)
	v_pk_mul_f32 v[18:19], v[22:23], v[18:19]
	v_lshlrev_b32_e32 v22, 16, v28
	v_and_b32_e32 v23, 0xffff0000, v28
	v_pk_mul_f32 v[18:19], v[18:19], v[22:23]
	v_pk_mul_f32 v[20:21], v[24:25], v[20:21]
	v_lshlrev_b32_e32 v22, 16, v29
	v_and_b32_e32 v23, 0xffff0000, v29
	v_pk_mul_f32 v[20:21], v[20:21], v[22:23]
	v_cvt_pk_bf16_f32 v18, v18, v19
	v_cvt_pk_bf16_f32 v19, v20, v21
	global_store_dwordx2 v[26:27], v[18:19], off offset:1024
	v_mov_b64_e32 v[22:23], v[210:211]
	s_nop 0
	v_mov_b64_e32 v[18:19], v[212:213]
	v_mov_b64_e32 v[20:21], v[214:215]
	v_pk_mul_f32 v[24:25], v[42:43], v[2:3] op_sel_hi:[1,0]
	v_pk_mul_f32 v[18:19], v[18:19], v[24:25]
	v_lshlrev_b32_e32 v24, 16, v22
	v_and_b32_e32 v25, 0xffff0000, v22
	v_pk_mul_f32 v[18:19], v[18:19], v[24:25]
	v_pk_mul_f32 v[24:25], v[44:45], v[2:3] op_sel_hi:[1,0]
	v_lshlrev_b32_e32 v22, 16, v23
	v_pk_mul_f32 v[20:21], v[20:21], v[24:25]
	v_and_b32_e32 v23, 0xffff0000, v23
	v_pk_mul_f32 v[20:21], v[20:21], v[22:23]
	v_cvt_pk_bf16_f32 v18, v18, v19
	v_cvt_pk_bf16_f32 v19, v20, v21
	global_store_dwordx2 v[6:7], v[18:19], off offset:32
	v_mov_b64_e32 v[22:23], v[216:217]
	s_nop 0
	v_mov_b64_e32 v[18:19], v[218:219]
	v_mov_b64_e32 v[20:21], v[220:221]
	v_pk_mul_f32 v[24:25], v[46:47], v[2:3] op_sel_hi:[1,0]
	v_pk_mul_f32 v[18:19], v[24:25], v[18:19]
	v_lshlrev_b32_e32 v24, 16, v22
	v_and_b32_e32 v25, 0xffff0000, v22
	v_pk_mul_f32 v[18:19], v[18:19], v[24:25]
	v_pk_mul_f32 v[24:25], v[48:49], v[2:3] op_sel_hi:[1,0]
	v_lshlrev_b32_e32 v22, 16, v23
	v_pk_mul_f32 v[20:21], v[24:25], v[20:21]
	v_and_b32_e32 v23, 0xffff0000, v23
	v_pk_mul_f32 v[20:21], v[20:21], v[22:23]
	v_cvt_pk_bf16_f32 v18, v18, v19
	v_cvt_pk_bf16_f32 v19, v20, v21
	global_store_dwordx2 v[6:7], v[18:19], off offset:64
	v_mov_b64_e32 v[22:23], v[222:223]
	s_nop 0
	v_mov_b64_e32 v[18:19], v[224:225]
	v_mov_b64_e32 v[20:21], v[226:227]
	v_mul_f32_e32 v2, v14, v14
	v_pk_mul_f32 v[10:11], v[10:11], v[18:19]
	v_lshlrev_b32_e32 v18, 16, v22
	v_and_b32_e32 v19, 0xffff0000, v22
	v_pk_mul_f32 v[10:11], v[10:11], v[18:19]
	v_pk_mul_f32 v[12:13], v[12:13], v[20:21]
	v_lshlrev_b32_e32 v18, 16, v23
	v_and_b32_e32 v19, 0xffff0000, v23
	v_pk_mul_f32 v[12:13], v[12:13], v[18:19]
	v_cvt_pk_bf16_f32 v10, v10, v11
	v_cvt_pk_bf16_f32 v11, v12, v13
	global_store_dwordx2 v[6:7], v[10:11], off offset:96
	v_pk_mul_f32 v[6:7], v[36:37], v[36:37]
	v_pk_mul_f32 v[10:11], v[34:35], v[34:35]
	s_nop 0
	v_pk_mov_b32 v[12:13], v[10:11], v[6:7] op_sel:[1,0]
	v_mov_b32_e32 v11, v7
	v_pk_add_f32 v[6:7], v[12:13], v[10:11]
	v_pk_mul_f32 v[10:11], v[32:33], v[32:33]
	v_pk_mul_f32 v[12:13], v[30:31], v[30:31]
	v_pk_add_f32 v[6:7], v[6:7], v[6:7] op_sel:[0,1] op_sel_hi:[1,0]
	v_pk_mov_b32 v[18:19], v[12:13], v[10:11] op_sel:[1,0]
	v_mov_b32_e32 v13, v11
	v_pk_add_f32 v[10:11], v[18:19], v[12:13]
	v_mul_f32_e32 v12, v15, v15
	v_pk_add_f32 v[10:11], v[10:11], v[10:11] op_sel:[0,1] op_sel_hi:[1,0]
	v_mov_b32_e32 v7, v2
	v_mov_b32_e32 v11, v12
	v_mul_f32_e32 v2, v39, v39
	v_mul_f32_e32 v13, v16, v16
	v_pk_add_f32 v[6:7], v[6:7], v[10:11]
	v_pk_fma_f32 v[10:11], v[38:39], v[38:39], v[2:3] op_sel_hi:[1,1,0]
	v_mul_f32_e32 v2, v41, v41
	v_mul_f32_e32 v18, v17, v17
	v_mov_b32_e32 v11, v13
	v_pk_fma_f32 v[12:13], v[40:41], v[40:41], v[2:3] op_sel_hi:[1,1,0]
	s_nop 0
	v_mov_b32_e32 v13, v18
	v_pk_add_f32 v[10:11], v[10:11], v[12:13]
	s_nop 0
	v_pk_add_f32 v[6:7], v[6:7], v[10:11]
	s_nop 0
	v_add_f32_e32 v2, v6, v7
	ds_bpermute_b32 v6, v8, v2
	s_waitcnt lgkmcnt(0)
	v_add_f32_e32 v2, v2, v6
	ds_bpermute_b32 v3, v3, v2
	s_waitcnt lgkmcnt(0)
	v_add_f32_e32 v2, v2, v3
	v_fmamk_f32 v2, v2, 0x3c800000, v236
	v_cmp_gt_f32_e32 vcc, s14, v2
	v_mul_f32_e32 v3, 0x4f800000, v2
	s_nop 0
	v_cndmask_b32_e32 v2, v2, v3, vcc
	v_sqrt_f32_e32 v3, v2
	s_nop 0
	v_add_u32_e32 v6, -1, v3
	v_fma_f32 v7, -v6, v3, v2
	v_cmp_ge_f32_e64 s[12:13], 0, v7
	v_add_u32_e32 v7, 1, v3
	s_nop 0
	v_cndmask_b32_e64 v6, v3, v6, s[12:13]
	v_fma_f32 v3, -v7, v3, v2
	v_cmp_lt_f32_e64 s[12:13], 0, v3
	s_nop 1
	v_cndmask_b32_e64 v3, v6, v7, s[12:13]
	v_mul_f32_e32 v6, 0x37800000, v3
	v_cndmask_b32_e32 v3, v3, v6, vcc
	v_cmp_class_f32_e32 vcc, v2, v237
	s_nop 1
	v_cndmask_b32_e32 v2, v3, v2, vcc
	v_div_scale_f32 v3, s[10:11], v2, v2, 1.0
	v_rcp_f32_e32 v6, v3
	s_nop 0
	v_fma_f32 v7, -v3, v6, 1.0
	v_fmac_f32_e32 v6, v7, v6
	v_div_scale_f32 v7, vcc, 1.0, v2, 1.0
	v_mul_f32_e32 v8, v7, v6
	v_fma_f32 v10, -v3, v8, v7
	v_fmac_f32_e32 v8, v10, v6
	v_fma_f32 v3, -v3, v8, v7
	v_div_fmas_f32 v3, v3, v6, v8
	v_div_fixup_f32 v6, v3, v2, 1.0
	v_or_b32_e32 v2, 16, v142
	v_ashrrev_i32_e32 v3, 31, v2
	v_lshlrev_b64 v[2:3], 11, v[2:3]
	v_lshl_add_u64 v[2:3], s[52:53], 0, v[2:3]
	v_lshl_add_u64 v[2:3], v[2:3], 0, s[82:83]
	v_lshl_add_u64 v[0:1], v[2:3], 0, v[0:1]
	v_add_co_u32_e32 v12, vcc, s15, v0
	v_lshl_add_u64 v[10:11], v[0:1], 0, s[16:17]
	s_nop 0
	v_addc_co_u32_e32 v13, vcc, 0, v1, vcc
	global_load_dwordx2 v[18:19], v[12:13], off offset:1024
	global_load_dwordx4 v[0:3], v[4:5], off
	global_load_dwordx2 v[210:211], v[10:11], off offset:32
	global_load_dwordx4 v[212:215], v[4:5], off offset:64
	global_load_dwordx2 v[216:217], v[10:11], off offset:64
	global_load_dwordx4 v[218:221], v[4:5], off offset:128
	global_load_dwordx2 v[222:223], v[10:11], off offset:96
	global_load_dwordx4 v[224:227], v[4:5], off offset:192
	v_pk_mul_f32 v[20:21], v[34:35], v[6:7] op_sel_hi:[1,0]
	s_waitcnt vmcnt(0)
	v_pk_mul_f32 v[0:1], v[0:1], v[20:21]
	v_lshlrev_b32_e32 v20, 16, v18
	v_and_b32_e32 v21, 0xffff0000, v18
	v_pk_mul_f32 v[0:1], v[0:1], v[20:21]
	v_pk_mul_f32 v[20:21], v[36:37], v[6:7] op_sel_hi:[1,0]
	v_lshlrev_b32_e32 v18, 16, v19
	v_pk_mul_f32 v[2:3], v[2:3], v[20:21]
	v_and_b32_e32 v19, 0xffff0000, v19
	v_pk_mul_f32 v[2:3], v[2:3], v[18:19]
	v_cvt_pk_bf16_f32 v0, v0, v1
	v_cvt_pk_bf16_f32 v1, v2, v3
	global_store_dwordx2 v[12:13], v[0:1], off offset:1024
	v_mov_b64_e32 v[12:13], v[210:211]
	s_nop 0
	v_mov_b64_e32 v[0:1], v[212:213]
	v_mov_b64_e32 v[2:3], v[214:215]
	v_pk_mul_f32 v[18:19], v[30:31], v[6:7] op_sel_hi:[1,0]
	v_pk_mul_f32 v[0:1], v[0:1], v[18:19]
	v_lshlrev_b32_e32 v18, 16, v12
	v_and_b32_e32 v19, 0xffff0000, v12
	v_pk_mul_f32 v[0:1], v[0:1], v[18:19]
	v_pk_mul_f32 v[18:19], v[32:33], v[6:7] op_sel_hi:[1,0]
	v_lshlrev_b32_e32 v12, 16, v13
	v_pk_mul_f32 v[2:3], v[2:3], v[18:19]
	v_and_b32_e32 v13, 0xffff0000, v13
	v_pk_mul_f32 v[2:3], v[2:3], v[12:13]
	v_cvt_pk_bf16_f32 v0, v0, v1
	v_cvt_pk_bf16_f32 v1, v2, v3
	global_store_dwordx2 v[10:11], v[0:1], off offset:32
	v_mov_b64_e32 v[12:13], v[216:217]
	s_nop 0
	v_mov_b64_e32 v[0:1], v[218:219]
	v_mov_b64_e32 v[2:3], v[220:221]
	v_pk_mul_f32 v[18:19], v[38:39], v[6:7] op_sel_hi:[1,0]
	v_pk_mul_f32 v[0:1], v[18:19], v[0:1]
	v_lshlrev_b32_e32 v18, 16, v12
	v_and_b32_e32 v19, 0xffff0000, v12
	v_pk_mul_f32 v[0:1], v[0:1], v[18:19]
	v_pk_mul_f32 v[18:19], v[40:41], v[6:7] op_sel_hi:[1,0]
	v_lshlrev_b32_e32 v12, 16, v13
	v_pk_mul_f32 v[2:3], v[18:19], v[2:3]
	v_and_b32_e32 v13, 0xffff0000, v13
	v_pk_mul_f32 v[2:3], v[2:3], v[12:13]
	v_cvt_pk_bf16_f32 v0, v0, v1
	v_cvt_pk_bf16_f32 v1, v2, v3
	global_store_dwordx2 v[10:11], v[0:1], off offset:64
	v_mov_b64_e32 v[12:13], v[222:223]
	s_nop 0
	v_mov_b64_e32 v[0:1], v[224:225]
	v_mov_b64_e32 v[2:3], v[226:227]
	v_pk_mul_f32 v[4:5], v[14:15], v[6:7] op_sel_hi:[1,0]
	v_pk_mul_f32 v[0:1], v[4:5], v[0:1]
	v_lshlrev_b32_e32 v4, 16, v12
	v_and_b32_e32 v5, 0xffff0000, v12
	v_pk_mul_f32 v[0:1], v[0:1], v[4:5]
	v_pk_mul_f32 v[4:5], v[16:17], v[6:7] op_sel_hi:[1,0]
	v_cvt_pk_bf16_f32 v0, v0, v1
	v_pk_mul_f32 v[2:3], v[4:5], v[2:3]
	v_lshlrev_b32_e32 v4, 16, v13
	v_and_b32_e32 v5, 0xffff0000, v13
	v_pk_mul_f32 v[2:3], v[2:3], v[4:5]
	s_nop 0
	v_cvt_pk_bf16_f32 v1, v2, v3
	global_store_dwordx2 v[10:11], v[0:1], off offset:96
	s_branch .LBB0_1095
